# nt hint on the retention KV-state stores (mixer-1 phase) and scanned R-state stores (each read once by a later phase) so they do not displace the projection buffer in the last-level cache
# speedup vs baseline: 1.0164x; 1.0007x over previous
.LBB0_184:
	s_add_i32 s15, s15, 32
	s_mov_b64 s[22:23], 0x80000
	v_add_co_u32_e32 v6, vcc, 0xe8f84000, v0
	s_nop 0
	v_addc_co_u32_e32 v7, vcc, -1, v1, vcc
	global_load_dword v8, v[6:7], off nt
	v_add_co_u32_e32 v6, vcc, 0xe8f88000, v0
	s_nop 0
	v_addc_co_u32_e32 v7, vcc, -1, v1, vcc
	global_load_dword v9, v[6:7], off nt
	v_add_co_u32_e32 v6, vcc, 0xe8f8c000, v0
	s_nop 0
	v_addc_co_u32_e32 v7, vcc, -1, v1, vcc
	global_load_dword v10, v[6:7], off nt
	v_add_co_u32_e32 v6, vcc, 0xe8f90000, v0
	s_nop 0
	v_addc_co_u32_e32 v7, vcc, -1, v1, vcc
	global_load_dword v11, v[6:7], off nt
	v_add_co_u32_e32 v6, vcc, 0xe8f94000, v0
	s_nop 0
	v_addc_co_u32_e32 v7, vcc, -1, v1, vcc
	global_load_dword v12, v[6:7], off nt
	v_add_co_u32_e32 v6, vcc, 0xe8f98000, v0
	s_nop 0
	v_addc_co_u32_e32 v7, vcc, -1, v1, vcc
	global_load_dword v13, v[6:7], off nt
	v_add_co_u32_e32 v6, vcc, 0xe8f9c000, v0
	s_nop 0
	v_addc_co_u32_e32 v7, vcc, -1, v1, vcc
	global_load_dword v14, v[6:7], off nt
	v_add_co_u32_e32 v6, vcc, 0xe8fa0000, v0
	s_nop 0
	v_addc_co_u32_e32 v7, vcc, -1, v1, vcc
	global_load_dword v15, v[6:7], off nt
	v_add_co_u32_e32 v6, vcc, 0xe8fa4000, v0
	s_nop 0
	v_addc_co_u32_e32 v7, vcc, -1, v1, vcc
	global_load_dword v16, v[6:7], off nt
	v_add_co_u32_e32 v6, vcc, 0xe8fa8000, v0
	s_nop 0
	v_addc_co_u32_e32 v7, vcc, -1, v1, vcc
	global_load_dword v17, v[6:7], off nt
	v_add_co_u32_e32 v6, vcc, 0xe8fac000, v0
	s_nop 0
	v_addc_co_u32_e32 v7, vcc, -1, v1, vcc
	global_load_dword v18, v[6:7], off nt
	v_add_co_u32_e32 v6, vcc, 0xe8fb0000, v0
	s_nop 0
	v_addc_co_u32_e32 v7, vcc, -1, v1, vcc
	global_load_dword v19, v[6:7], off nt
	v_add_co_u32_e32 v6, vcc, 0xe8fb4000, v0
	s_nop 0
	v_addc_co_u32_e32 v7, vcc, -1, v1, vcc
	global_load_dword v20, v[6:7], off nt
	v_add_co_u32_e32 v6, vcc, 0xe8fb8000, v0
	s_nop 0
	v_addc_co_u32_e32 v7, vcc, -1, v1, vcc
	global_load_dword v21, v[6:7], off nt
	v_add_co_u32_e32 v6, vcc, 0xe8fbc000, v0
	s_nop 0
	v_addc_co_u32_e32 v7, vcc, -1, v1, vcc
	global_load_dword v22, v[6:7], off nt
	v_add_co_u32_e32 v6, vcc, 0xe8fc0000, v0
	s_nop 0
	v_addc_co_u32_e32 v7, vcc, -1, v1, vcc
	global_load_dword v23, v[6:7], off nt
	v_add_co_u32_e32 v6, vcc, 0xe8fc4000, v0
	s_nop 0
	v_addc_co_u32_e32 v7, vcc, -1, v1, vcc
	global_load_dword v24, v[6:7], off nt
	v_add_co_u32_e32 v6, vcc, 0xe8fc8000, v0
	s_nop 0
	v_addc_co_u32_e32 v7, vcc, -1, v1, vcc
	global_load_dword v25, v[6:7], off nt
	v_add_co_u32_e32 v6, vcc, 0xe8fcc000, v0
	s_nop 0
	v_addc_co_u32_e32 v7, vcc, -1, v1, vcc
	global_load_dword v26, v[6:7], off nt
	v_add_co_u32_e32 v6, vcc, 0xe8fd0000, v0
	s_nop 0
	v_addc_co_u32_e32 v7, vcc, -1, v1, vcc
	global_load_dword v27, v[6:7], off nt
	v_add_co_u32_e32 v6, vcc, 0xe8fd4000, v0
	s_nop 0
	v_addc_co_u32_e32 v7, vcc, -1, v1, vcc
	global_load_dword v28, v[6:7], off nt
	v_add_co_u32_e32 v6, vcc, 0xe8fd8000, v0
	s_nop 0
	v_addc_co_u32_e32 v7, vcc, -1, v1, vcc
	global_load_dword v29, v[6:7], off nt
	v_add_co_u32_e32 v6, vcc, 0xe8fdc000, v0
	s_nop 0
	v_addc_co_u32_e32 v7, vcc, -1, v1, vcc
	global_load_dword v30, v[6:7], off nt
	v_add_co_u32_e32 v6, vcc, 0xe8fe0000, v0
	s_nop 0
	v_addc_co_u32_e32 v7, vcc, -1, v1, vcc
	global_load_dword v31, v[6:7], off nt
	v_add_co_u32_e32 v6, vcc, 0xe8fe4000, v0
	s_nop 0
	v_addc_co_u32_e32 v7, vcc, -1, v1, vcc
	global_load_dword v32, v[6:7], off nt
	v_add_co_u32_e32 v6, vcc, 0xe8fe8000, v0
	s_nop 0
	v_addc_co_u32_e32 v7, vcc, -1, v1, vcc
	global_load_dword v34, v[6:7], off nt
	v_add_co_u32_e32 v6, vcc, 0xe8fec000, v0
	s_nop 0
	v_addc_co_u32_e32 v7, vcc, -1, v1, vcc
	global_load_dword v35, v[6:7], off nt
	v_add_co_u32_e32 v6, vcc, 0xe8ff0000, v0
	s_nop 0
	v_addc_co_u32_e32 v7, vcc, -1, v1, vcc
	global_load_dword v36, v[6:7], off nt
	v_add_co_u32_e32 v6, vcc, 0xe8ff4000, v0
	s_nop 0
	v_addc_co_u32_e32 v7, vcc, -1, v1, vcc
	global_load_dword v37, v[6:7], off nt
	v_add_co_u32_e32 v6, vcc, 0xe8ff8000, v0
	s_nop 0
	v_addc_co_u32_e32 v7, vcc, -1, v1, vcc
	global_load_dword v39, v[6:7], off nt
	v_add_co_u32_e32 v6, vcc, 0xe8ffc000, v0
	s_nop 0
	v_addc_co_u32_e32 v7, vcc, -1, v1, vcc
	global_load_dword v40, v[6:7], off nt
	v_add_co_u32_e32 v6, vcc, 0xe9000000, v0
	s_nop 0
	v_addc_co_u32_e32 v7, vcc, -1, v1, vcc
	global_load_dword v41, v[6:7], off nt
	s_waitcnt vmcnt(0)
	v_fmac_f32_e32 v8, v4, v5
	v_fmac_f32_e32 v9, v4, v8
	v_fmac_f32_e32 v10, v4, v9
	v_fmac_f32_e32 v11, v4, v10
	v_fmac_f32_e32 v12, v4, v11
	v_fmac_f32_e32 v13, v4, v12
	v_fmac_f32_e32 v14, v4, v13
	v_fmac_f32_e32 v15, v4, v14
	v_fmac_f32_e32 v16, v4, v15
	v_fmac_f32_e32 v17, v4, v16
	v_fmac_f32_e32 v18, v4, v17
	v_fmac_f32_e32 v19, v4, v18
	v_fmac_f32_e32 v20, v4, v19
	v_fmac_f32_e32 v21, v4, v20
	v_fmac_f32_e32 v22, v4, v21
	v_fmac_f32_e32 v23, v4, v22
	v_fmac_f32_e32 v24, v4, v23
	v_fmac_f32_e32 v25, v4, v24
	v_fmac_f32_e32 v26, v4, v25
	v_fmac_f32_e32 v27, v4, v26
	v_fmac_f32_e32 v28, v4, v27
	v_fmac_f32_e32 v29, v4, v28
	v_fmac_f32_e32 v30, v4, v29
	v_fmac_f32_e32 v31, v4, v30
	v_fmac_f32_e32 v32, v4, v31
	v_fmac_f32_e32 v34, v4, v32
	v_fmac_f32_e32 v35, v4, v34
	v_fmac_f32_e32 v36, v4, v35
	v_fmac_f32_e32 v37, v4, v36
	v_fmac_f32_e32 v39, v4, v37
	v_fmac_f32_e32 v40, v4, v39
	v_fmac_f32_e32 v41, v4, v40
	v_add_co_u32_e32 v6, vcc, 0xfff84000, v0
	s_nop 0
	v_addc_co_u32_e32 v7, vcc, -1, v1, vcc
	s_nop 0
	global_store_dword v[6:7], v5, off nt
	v_add_co_u32_e32 v6, vcc, 0xfff88000, v0
	s_nop 0
	v_addc_co_u32_e32 v7, vcc, -1, v1, vcc
	s_nop 0
	global_store_dword v[6:7], v8, off nt
	v_add_co_u32_e32 v6, vcc, 0xfff8c000, v0
	s_nop 0
	v_addc_co_u32_e32 v7, vcc, -1, v1, vcc
	s_nop 0
	global_store_dword v[6:7], v9, off nt
	global_store_dword v[0:1], v40, off nt
	v_add_co_u32_e32 v6, vcc, 0xfff90000, v0
	s_nop 0
	v_addc_co_u32_e32 v7, vcc, -1, v1, vcc
	s_nop 0
	global_store_dword v[6:7], v10, off nt
	v_add_co_u32_e32 v6, vcc, 0xfff94000, v0
	s_nop 0
	v_addc_co_u32_e32 v7, vcc, -1, v1, vcc
	s_nop 0
	global_store_dword v[6:7], v11, off nt
	v_add_co_u32_e32 v6, vcc, 0xfff98000, v0
	s_nop 0
	v_addc_co_u32_e32 v7, vcc, -1, v1, vcc
	s_nop 0
	global_store_dword v[6:7], v12, off nt
	v_add_co_u32_e32 v6, vcc, 0xfff9c000, v0
	s_nop 0
	v_addc_co_u32_e32 v7, vcc, -1, v1, vcc
	s_nop 0
	global_store_dword v[6:7], v13, off nt
	v_add_co_u32_e32 v6, vcc, 0xfffa0000, v0
	s_nop 0
	v_addc_co_u32_e32 v7, vcc, -1, v1, vcc
	s_nop 0
	global_store_dword v[6:7], v14, off nt
	v_add_co_u32_e32 v6, vcc, 0xfffa4000, v0
	s_nop 0
	v_addc_co_u32_e32 v7, vcc, -1, v1, vcc
	s_nop 0
	global_store_dword v[6:7], v15, off nt
	v_add_co_u32_e32 v6, vcc, 0xfffa8000, v0
	s_nop 0
	v_addc_co_u32_e32 v7, vcc, -1, v1, vcc
	s_nop 0
	global_store_dword v[6:7], v16, off nt
	v_add_co_u32_e32 v6, vcc, 0xfffac000, v0
	s_nop 0
	v_addc_co_u32_e32 v7, vcc, -1, v1, vcc
	s_nop 0
	global_store_dword v[6:7], v17, off nt
	v_add_co_u32_e32 v6, vcc, 0xfffb0000, v0
	s_nop 0
	v_addc_co_u32_e32 v7, vcc, -1, v1, vcc
	s_nop 0
	global_store_dword v[6:7], v18, off nt
	v_add_co_u32_e32 v6, vcc, 0xfffb4000, v0
	s_nop 0
	v_addc_co_u32_e32 v7, vcc, -1, v1, vcc
	s_nop 0
	global_store_dword v[6:7], v19, off nt
	v_add_co_u32_e32 v6, vcc, 0xfffb8000, v0
	s_nop 0
	v_addc_co_u32_e32 v7, vcc, -1, v1, vcc
	s_nop 0
	global_store_dword v[6:7], v20, off nt
	v_add_co_u32_e32 v6, vcc, 0xfffbc000, v0
	s_nop 0
	v_addc_co_u32_e32 v7, vcc, -1, v1, vcc
	s_nop 0
	global_store_dword v[6:7], v21, off nt
	v_add_co_u32_e32 v6, vcc, 0xfffc0000, v0
	s_nop 0
	v_addc_co_u32_e32 v7, vcc, -1, v1, vcc
	s_nop 0
	global_store_dword v[6:7], v22, off nt
	v_add_co_u32_e32 v6, vcc, 0xfffc4000, v0
	s_nop 0
	v_addc_co_u32_e32 v7, vcc, -1, v1, vcc
	s_nop 0
	global_store_dword v[6:7], v23, off nt
	v_add_co_u32_e32 v6, vcc, 0xfffc8000, v0
	s_nop 0
	v_addc_co_u32_e32 v7, vcc, -1, v1, vcc
	s_nop 0
	global_store_dword v[6:7], v24, off nt
	v_add_co_u32_e32 v6, vcc, 0xfffcc000, v0
	s_nop 0
	v_addc_co_u32_e32 v7, vcc, -1, v1, vcc
	s_nop 0
	global_store_dword v[6:7], v25, off nt
	v_add_co_u32_e32 v6, vcc, 0xfffd0000, v0
	s_nop 0
	v_addc_co_u32_e32 v7, vcc, -1, v1, vcc
	s_nop 0
	global_store_dword v[6:7], v26, off nt
	v_add_co_u32_e32 v6, vcc, 0xfffd4000, v0
	s_nop 0
	v_addc_co_u32_e32 v7, vcc, -1, v1, vcc
	s_nop 0
	global_store_dword v[6:7], v27, off nt
	v_add_co_u32_e32 v6, vcc, 0xfffd8000, v0
	s_nop 0
	v_addc_co_u32_e32 v7, vcc, -1, v1, vcc
	s_nop 0
	global_store_dword v[6:7], v28, off nt
	v_add_co_u32_e32 v6, vcc, 0xfffdc000, v0
	s_nop 0
	v_addc_co_u32_e32 v7, vcc, -1, v1, vcc
	s_nop 0
	global_store_dword v[6:7], v29, off nt
	v_add_co_u32_e32 v6, vcc, 0xfffe0000, v0
	s_nop 0
	v_addc_co_u32_e32 v7, vcc, -1, v1, vcc
	s_nop 0
	global_store_dword v[6:7], v30, off nt
	v_add_co_u32_e32 v6, vcc, 0xfffe4000, v0
	s_nop 0
	v_addc_co_u32_e32 v7, vcc, -1, v1, vcc
	s_nop 0
	global_store_dword v[6:7], v31, off nt
	v_add_co_u32_e32 v6, vcc, 0xfffe8000, v0
	s_nop 0
	v_addc_co_u32_e32 v7, vcc, -1, v1, vcc
	s_nop 0
	global_store_dword v[6:7], v32, off nt
	v_add_co_u32_e32 v6, vcc, 0xfffec000, v0
	s_nop 0
	v_addc_co_u32_e32 v7, vcc, -1, v1, vcc
	s_nop 0
	global_store_dword v[6:7], v34, off nt
	v_add_co_u32_e32 v6, vcc, 0xffff0000, v0
	s_nop 0
	v_addc_co_u32_e32 v7, vcc, -1, v1, vcc
	s_nop 0
	global_store_dword v[6:7], v35, off nt
	v_add_co_u32_e32 v6, vcc, 0xffff4000, v0
	s_nop 0
	v_addc_co_u32_e32 v7, vcc, -1, v1, vcc
	s_nop 0
	global_store_dword v[6:7], v36, off nt
	v_add_co_u32_e32 v6, vcc, 0xffff8000, v0
	s_nop 0
	v_addc_co_u32_e32 v7, vcc, -1, v1, vcc
	s_nop 0
	global_store_dword v[6:7], v37, off nt
	v_add_co_u32_e32 v6, vcc, 0xffffc000, v0
	s_nop 0
	v_addc_co_u32_e32 v7, vcc, -1, v1, vcc
	s_nop 0
	global_store_dword v[6:7], v39, off nt
	v_mov_b32_e32 v5, v41
	v_lshl_add_u64 v[0:1], v[0:1], 0, s[22:23]
	s_cmpk_gt_u32 s15, 0xdf
	s_cbranch_scc0 .LBB0_184
	v_add_u32_e32 v2, s12, v2
	s_mov_b32 s15, 0xbfff
	v_cmp_lt_i32_e32 vcc, s15, v2
	s_or_b64 s[20:21], vcc, s[20:21]
	v_add_u16_e32 v3, s12, v3
	s_andn2_b64 exec, exec, s[20:21]
	s_cbranch_execnz .LBB0_183

.LBB0_341:
	s_ashr_i32 s37, s36, 31
	s_lshr_b32 s0, s37, 24
	s_add_i32 s0, s36, s0
	s_mul_hi_i32 s1, s36, 0x2aaaaaab
	s_ashr_i32 s15, s0, 8
	s_lshr_b32 s17, s1, 31
	s_ashr_i32 s1, s1, 8
	s_add_i32 s20, s1, s17
	s_mul_hi_i32 s1, s15, 0x2aaaaaab
	s_lshr_b32 s17, s1, 31
	s_add_i32 s1, s1, s17
	s_mul_i32 s1, s1, 6
	s_sub_i32 s26, s15, s1
	s_and_b32 s0, s0, 0xffffff00
	v_cvt_f32_i32_e32 v0, s26
	s_sub_i32 s0, s36, s0
	s_ashr_i32 s21, s20, 31
	s_ashr_i32 s1, s0, 31
	s_lshl_b64 s[20:21], s[20:21], 14
	s_lshl_b64 s[0:1], s[0:1], 6
	s_add_u32 s20, s20, s0
	v_sub_f32_e32 v0, 0xc0a00000, v0
	s_addc_u32 s17, s21, s1
	v_cmp_gt_f32_e64 s[0:1], s47, v0
	v_mov_b32_e32 v51, v33
	v_mov_b32_e32 v53, v33
	v_cndmask_b32_e64 v1, 0, v229, s[0:1]
	v_add_f32_e32 v0, v0, v1
	v_exp_f32_e32 v0, v0
	s_and_b64 s[0:1], s[0:1], exec
	s_cselect_b32 s0, 0xffffffc0, 0
	v_mov_b32_e32 v55, v33
	v_ldexp_f32 v0, v0, s0
	v_sub_f32_e32 v0, 1.0, v0
	v_cmp_gt_f32_e64 s[0:1], s33, v0
	s_and_b64 s[22:23], s[0:1], exec
	s_cselect_b32 s21, 32, 0
	v_ldexp_f32 v0, v0, s21
	v_log_f32_e32 v0, v0
	v_cndmask_b32_e64 v1, 0, v246, s[0:1]
	s_mul_i32 s0, s17, 0x1800
	s_mul_hi_u32 s1, s20, 0x1800
	s_add_i32 s1, s1, s0
	s_mul_i32 s0, s20, 0x1800
	s_add_u32 s21, s42, s0
	v_sub_f32_e32 v61, v0, v1
	s_addc_u32 s23, s43, s1
	s_lshl_b32 s0, s26, 6
	s_ashr_i32 s1, s0, 31
	v_mul_f32_e32 v0, 0x427c0000, v61
	s_lshl_b64 s[38:39], s[0:1], 1
	v_cmp_gt_f32_e64 s[0:1], s47, v0
	s_add_u32 s22, s21, s38
	s_addc_u32 s23, s23, s39
	v_cndmask_b32_e64 v0, 0, v229, s[0:1]
	v_fmac_f32_e32 v0, 0x427c0000, v61
	v_exp_f32_e32 v0, v0
	s_and_b64 s[0:1], s[0:1], exec
	s_cselect_b32 s0, 0xffffffc0, 0
	v_mov_b32_e32 v57, v33
	v_ldexp_f32 v74, v0, s0
	v_lshl_add_u64 v[0:1], s[22:23], 0, v[32:33]
	s_mov_b64 s[0:1], 0x1100
	v_lshl_add_u64 v[70:71], v[0:1], 0, s[0:1]
	v_lshl_add_u64 v[12:13], v[70:71], 0, v[50:51]
	global_load_dwordx4 v[0:3], v[12:13], off
	v_add_co_u32_e64 v4, s[0:1], s41, v12
	v_lshl_add_u64 v[16:17], v[70:71], 0, v[52:53]
	s_nop 0
	v_addc_co_u32_e64 v5, s[0:1], 0, v13, s[0:1]
	global_load_dwordx4 v[4:7], v[4:5], off
	v_add_co_u32_e64 v8, s[0:1], s40, v12
	global_load_dwordx4 v[16:19], v[16:17], off
	s_nop 0
	v_addc_co_u32_e64 v9, s[0:1], 0, v13, s[0:1]
	global_load_dwordx4 v[8:11], v[8:9], off
	v_add_co_u32_e64 v12, s[0:1], s44, v12
	v_lshl_add_u64 v[20:21], v[70:71], 0, v[54:55]
	s_nop 0
	v_addc_co_u32_e64 v13, s[0:1], 0, v13, s[0:1]
	global_load_dwordx4 v[12:15], v[12:13], off
	v_mul_f32_e64 v51, v25, -v61
	global_load_dwordx4 v[20:23], v[20:21], off
	v_exp_f32_e32 v51, v51
	v_lshl_add_u64 v[66:67], v[70:71], 0, v[56:57]
	global_load_dwordx4 v[66:69], v[66:67], off
	v_mov_b32_e32 v59, v33
	v_mul_f32_e32 v51, v74, v51
	v_lshl_add_u64 v[70:71], v[70:71], 0, v[58:59]
	global_load_dwordx4 v[70:73], v[70:71], off
	s_waitcnt vmcnt(7)
	v_lshlrev_b32_e32 v53, 16, v0
	v_and_b32_e32 v0, 0xffff0000, v0
	v_mul_f32_e32 v53, v51, v53
	v_mul_f32_e32 v0, v51, v0
	v_cvt_pk_bf16_f32 v0, v53, v0
	v_lshlrev_b32_e32 v53, 16, v1
	v_and_b32_e32 v1, 0xffff0000, v1
	v_mul_f32_e32 v53, v51, v53
	v_mul_f32_e32 v1, v51, v1
	v_cvt_pk_bf16_f32 v1, v53, v1
	v_lshlrev_b32_e32 v53, 16, v2
	v_and_b32_e32 v2, 0xffff0000, v2
	v_mul_f32_e32 v53, v51, v53
	v_mul_f32_e32 v2, v51, v2
	v_cvt_pk_bf16_f32 v2, v53, v2
	v_lshlrev_b32_e32 v53, 16, v3
	v_and_b32_e32 v3, 0xffff0000, v3
	v_mul_f32_e32 v3, v51, v3
	v_mul_f32_e32 v53, v51, v53
	v_cvt_pk_bf16_f32 v3, v53, v3
	ds_write_b16 v29, v0 offset:9216
	ds_write_b16_d16_hi v29, v0 offset:9360
	ds_write_b16 v29, v1 offset:9504
	ds_write_b16_d16_hi v29, v1 offset:9648
	ds_write_b16 v29, v2 offset:9792
	ds_write_b16_d16_hi v29, v2 offset:9936
	ds_write_b16 v29, v3 offset:10080
	ds_write_b16_d16_hi v29, v3 offset:10224
	v_mul_f32_e64 v0, v31, -v61
	v_exp_f32_e32 v0, v0
	s_waitcnt vmcnt(6)
	v_lshlrev_b32_e32 v1, 16, v4
	v_and_b32_e32 v2, 0xffff0000, v4
	v_and_b32_e32 v3, 0xffff0000, v5
	v_mul_f32_e32 v0, v74, v0
	v_mul_f32_e32 v1, v0, v1
	v_mul_f32_e32 v2, v0, v2
	v_cvt_pk_bf16_f32 v1, v1, v2
	v_lshlrev_b32_e32 v2, 16, v5
	v_mul_f32_e32 v2, v0, v2
	v_mul_f32_e32 v3, v0, v3
	v_cvt_pk_bf16_f32 v2, v2, v3
	v_lshlrev_b32_e32 v3, 16, v6
	v_and_b32_e32 v4, 0xffff0000, v6
	v_mul_f32_e32 v3, v0, v3
	v_mul_f32_e32 v4, v0, v4
	v_cvt_pk_bf16_f32 v3, v3, v4
	v_lshlrev_b32_e32 v4, 16, v7
	v_and_b32_e32 v5, 0xffff0000, v7
	v_mul_f32_e32 v4, v0, v4
	v_mul_f32_e32 v0, v0, v5
	v_cvt_pk_bf16_f32 v0, v4, v0
	ds_write_b16 v29, v1 offset:9232
	ds_write_b16_d16_hi v29, v1 offset:9376
	ds_write_b16 v29, v2 offset:9520
	ds_write_b16_d16_hi v29, v2 offset:9664
	ds_write_b16 v29, v3 offset:9808
	ds_write_b16_d16_hi v29, v3 offset:9952
	ds_write_b16 v29, v0 offset:10096
	ds_write_b16_d16_hi v29, v0 offset:10240
	v_mul_f32_e64 v0, v35, -v61
	v_exp_f32_e32 v0, v0
	s_waitcnt vmcnt(4)
	v_lshlrev_b32_e32 v1, 16, v8
	v_and_b32_e32 v2, 0xffff0000, v8
	v_and_b32_e32 v3, 0xffff0000, v9
	v_mul_f32_e32 v0, v74, v0
	v_mul_f32_e32 v1, v0, v1
	v_mul_f32_e32 v2, v0, v2
	v_cvt_pk_bf16_f32 v1, v1, v2
	v_lshlrev_b32_e32 v2, 16, v9
	v_mul_f32_e32 v2, v0, v2
	v_mul_f32_e32 v3, v0, v3
	v_cvt_pk_bf16_f32 v2, v2, v3
	v_lshlrev_b32_e32 v3, 16, v10
	v_and_b32_e32 v4, 0xffff0000, v10
	v_mul_f32_e32 v3, v0, v3
	v_mul_f32_e32 v4, v0, v4
	v_cvt_pk_bf16_f32 v3, v3, v4
	v_lshlrev_b32_e32 v4, 16, v11
	v_and_b32_e32 v5, 0xffff0000, v11
	v_mul_f32_e32 v4, v0, v4
	v_mul_f32_e32 v0, v0, v5
	v_cvt_pk_bf16_f32 v0, v4, v0
	ds_write_b16 v29, v1 offset:9248
	ds_write_b16_d16_hi v29, v1 offset:9392
	ds_write_b16 v29, v2 offset:9536
	ds_write_b16_d16_hi v29, v2 offset:9680
	ds_write_b16 v29, v3 offset:9824
	ds_write_b16_d16_hi v29, v3 offset:9968
	ds_write_b16 v29, v0 offset:10112
	ds_write_b16_d16_hi v29, v0 offset:10256
	v_mul_f32_e64 v0, v37, -v61
	v_exp_f32_e32 v0, v0
	s_waitcnt vmcnt(3)
	v_lshlrev_b32_e32 v1, 16, v12
	v_and_b32_e32 v2, 0xffff0000, v12
	v_and_b32_e32 v3, 0xffff0000, v13
	v_mul_f32_e32 v0, v74, v0
	v_mul_f32_e32 v1, v0, v1
	v_mul_f32_e32 v2, v0, v2
	v_cvt_pk_bf16_f32 v1, v1, v2
	v_lshlrev_b32_e32 v2, 16, v13
	v_mul_f32_e32 v2, v0, v2
	v_mul_f32_e32 v3, v0, v3
	v_cvt_pk_bf16_f32 v2, v2, v3
	v_lshlrev_b32_e32 v3, 16, v14
	v_and_b32_e32 v4, 0xffff0000, v14
	v_mul_f32_e32 v3, v0, v3
	v_mul_f32_e32 v4, v0, v4
	v_cvt_pk_bf16_f32 v3, v3, v4
	v_lshlrev_b32_e32 v4, 16, v15
	v_and_b32_e32 v5, 0xffff0000, v15
	v_mul_f32_e32 v4, v0, v4
	v_mul_f32_e32 v0, v0, v5
	v_cvt_pk_bf16_f32 v0, v4, v0
	ds_write_b16 v29, v1 offset:9264
	ds_write_b16_d16_hi v29, v1 offset:9408
	ds_write_b16 v29, v2 offset:9552
	ds_write_b16_d16_hi v29, v2 offset:9696
	ds_write_b16 v29, v3 offset:9840
	ds_write_b16_d16_hi v29, v3 offset:9984
	ds_write_b16 v29, v0 offset:10128
	ds_write_b16_d16_hi v29, v0 offset:10272
	v_mul_f32_e64 v0, v39, -v61
	v_exp_f32_e32 v0, v0
	v_lshlrev_b32_e32 v1, 16, v16
	v_and_b32_e32 v2, 0xffff0000, v16
	v_and_b32_e32 v3, 0xffff0000, v17
	v_mul_f32_e32 v0, v74, v0
	v_mul_f32_e32 v1, v0, v1
	v_mul_f32_e32 v2, v0, v2
	v_cvt_pk_bf16_f32 v1, v1, v2
	v_lshlrev_b32_e32 v2, 16, v17
	v_mul_f32_e32 v2, v0, v2
	v_mul_f32_e32 v3, v0, v3
	v_cvt_pk_bf16_f32 v2, v2, v3
	v_lshlrev_b32_e32 v3, 16, v18
	v_and_b32_e32 v4, 0xffff0000, v18
	v_mul_f32_e32 v3, v0, v3
	v_mul_f32_e32 v4, v0, v4
	v_cvt_pk_bf16_f32 v3, v3, v4
	v_lshlrev_b32_e32 v4, 16, v19
	v_and_b32_e32 v5, 0xffff0000, v19
	v_mul_f32_e32 v4, v0, v4
	v_mul_f32_e32 v0, v0, v5
	v_cvt_pk_bf16_f32 v0, v4, v0
	ds_write_b16 v29, v1 offset:9280
	ds_write_b16_d16_hi v29, v1 offset:9424
	ds_write_b16 v29, v2 offset:9568
	ds_write_b16_d16_hi v29, v2 offset:9712
	ds_write_b16 v29, v3 offset:9856
	ds_write_b16_d16_hi v29, v3 offset:10000
	ds_write_b16 v29, v0 offset:10144
	ds_write_b16_d16_hi v29, v0 offset:10288
	v_mul_f32_e64 v0, v41, -v61
	v_exp_f32_e32 v0, v0
	s_waitcnt vmcnt(2)
	v_lshlrev_b32_e32 v1, 16, v20
	v_and_b32_e32 v2, 0xffff0000, v20
	v_and_b32_e32 v3, 0xffff0000, v21
	v_mul_f32_e32 v0, v74, v0
	v_mul_f32_e32 v1, v0, v1
	v_mul_f32_e32 v2, v0, v2
	v_cvt_pk_bf16_f32 v1, v1, v2
	v_lshlrev_b32_e32 v2, 16, v21
	v_mul_f32_e32 v2, v0, v2
	v_mul_f32_e32 v3, v0, v3
	v_cvt_pk_bf16_f32 v2, v2, v3
	v_lshlrev_b32_e32 v3, 16, v22
	v_and_b32_e32 v4, 0xffff0000, v22
	v_mul_f32_e32 v3, v0, v3
	v_mul_f32_e32 v4, v0, v4
	v_cvt_pk_bf16_f32 v3, v3, v4
	v_lshlrev_b32_e32 v4, 16, v23
	v_and_b32_e32 v5, 0xffff0000, v23
	v_mul_f32_e32 v4, v0, v4
	v_mul_f32_e32 v0, v0, v5
	v_cvt_pk_bf16_f32 v0, v4, v0
	ds_write_b16 v29, v1 offset:9296
	ds_write_b16_d16_hi v29, v1 offset:9440
	ds_write_b16 v29, v2 offset:9584
	ds_write_b16_d16_hi v29, v2 offset:9728
	ds_write_b16 v29, v3 offset:9872
	ds_write_b16_d16_hi v29, v3 offset:10016
	ds_write_b16 v29, v0 offset:10160
	ds_write_b16_d16_hi v29, v0 offset:10304
	v_mul_f32_e64 v0, v43, -v61
	v_exp_f32_e32 v0, v0
	s_waitcnt vmcnt(1)
	v_lshlrev_b32_e32 v1, 16, v66
	v_and_b32_e32 v2, 0xffff0000, v66
	v_and_b32_e32 v3, 0xffff0000, v67
	v_mul_f32_e32 v0, v74, v0
	v_mul_f32_e32 v1, v0, v1
	v_mul_f32_e32 v2, v0, v2
	v_cvt_pk_bf16_f32 v1, v1, v2
	v_lshlrev_b32_e32 v2, 16, v67
	v_mul_f32_e32 v2, v0, v2
	v_mul_f32_e32 v3, v0, v3
	v_cvt_pk_bf16_f32 v2, v2, v3
	v_lshlrev_b32_e32 v3, 16, v68
	v_and_b32_e32 v4, 0xffff0000, v68
	v_mul_f32_e32 v3, v0, v3
	v_mul_f32_e32 v4, v0, v4
	v_cvt_pk_bf16_f32 v3, v3, v4
	v_lshlrev_b32_e32 v4, 16, v69
	v_and_b32_e32 v5, 0xffff0000, v69
	v_mul_f32_e32 v4, v0, v4
	v_mul_f32_e32 v0, v0, v5
	v_cvt_pk_bf16_f32 v0, v4, v0
	ds_write_b16 v29, v1 offset:9312
	ds_write_b16_d16_hi v29, v1 offset:9456
	ds_write_b16 v29, v2 offset:9600
	ds_write_b16_d16_hi v29, v2 offset:9744
	ds_write_b16 v29, v3 offset:9888
	ds_write_b16_d16_hi v29, v3 offset:10032
	ds_write_b16 v29, v0 offset:10176
	ds_write_b16_d16_hi v29, v0 offset:10320
	v_mul_f32_e64 v0, v62, -v61
	v_exp_f32_e32 v0, v0
	s_waitcnt vmcnt(0)
	v_lshlrev_b32_e32 v1, 16, v70
	v_and_b32_e32 v2, 0xffff0000, v70
	v_and_b32_e32 v3, 0xffff0000, v71
	v_mul_f32_e32 v0, v74, v0
	v_mul_f32_e32 v1, v0, v1
	v_mul_f32_e32 v2, v0, v2
	v_cvt_pk_bf16_f32 v1, v1, v2
	v_lshlrev_b32_e32 v2, 16, v71
	v_mul_f32_e32 v2, v0, v2
	v_mul_f32_e32 v3, v0, v3
	v_cvt_pk_bf16_f32 v2, v2, v3
	v_lshlrev_b32_e32 v3, 16, v72
	v_and_b32_e32 v4, 0xffff0000, v72
	v_mul_f32_e32 v3, v0, v3
	v_mul_f32_e32 v4, v0, v4
	v_cvt_pk_bf16_f32 v3, v3, v4
	v_lshlrev_b32_e32 v4, 16, v73
	v_and_b32_e32 v5, 0xffff0000, v73
	v_mul_f32_e32 v4, v0, v4
	v_mul_f32_e32 v0, v0, v5
	v_cvt_pk_bf16_f32 v0, v4, v0
	ds_write_b16 v29, v1 offset:9328
	ds_write_b16_d16_hi v29, v1 offset:9472
	ds_write_b16 v29, v2 offset:9616
	ds_write_b16_d16_hi v29, v2 offset:9760
	ds_write_b16 v29, v3 offset:9904
	ds_write_b16_d16_hi v29, v3 offset:10048
	ds_write_b16 v29, v0 offset:10192
	ds_write_b16_d16_hi v29, v0 offset:10336
	v_or_b32_e32 v0, s20, v24
	v_mov_b64_e32 v[2:3], s[42:43]
	v_mad_u64_u32 v[0:1], s[0:1], v0, s5, v[2:3]
	v_mad_i32_i24 v1, s17, v207, v1
	v_lshl_add_u64 v[0:1], v[0:1], 0, s[38:39]
	v_mov_b32_e32 v61, v33
	v_lshl_add_u64 v[0:1], v[0:1], 0, v[60:61]
	s_lshl_b32 s0, s15, 14
	v_mov_b64_e32 v[152:153], v[0:1]
	global_load_dwordx4 v[4:7], v[0:1], off offset:3584
	global_load_dwordx4 v[8:11], v[0:1], off offset:3648
	v_subrev_u32_e32 v0, s0, v63
	v_subrev_u32_e32 v12, 56, v0
	v_ashrrev_i32_e32 v13, 31, v12
	v_lshlrev_b64 v[12:13], 7, v[12:13]
	v_lshl_add_u64 v[16:17], v[44:45], 0, v[12:13]
	v_lshl_add_u64 v[66:67], v[46:47], 0, v[12:13]
	v_mov_b64_e32 v[154:155], v[16:17]
	global_load_dwordx4 v[12:15], v[16:17], off offset:16
	s_nop 0
	global_load_dwordx4 v[16:19], v[16:17], off
	s_nop 0
	v_mov_b64_e32 v[156:157], v[66:67]
	global_load_dwordx4 v[20:23], v[66:67], off offset:16
	s_nop 0
	global_load_dwordx4 v[66:69], v[66:67], off
	s_mov_b32 s98, 0xc000
	s_mov_b32 s99, 0
	v_lshl_add_u64 v[158:159], s[98:99], 0, v[152:153]
	global_load_dwordx4 v[92:95], v[158:159], off offset:3584
	global_load_dwordx4 v[96:99], v[158:159], off offset:3648
	global_load_dwordx4 v[100:103], v[154:155], off offset:1040
	global_load_dwordx4 v[104:107], v[154:155], off offset:1024
	global_load_dwordx4 v[108:111], v[156:157], off offset:1040
	global_load_dwordx4 v[112:115], v[156:157], off offset:1024
	s_mov_b32 s98, 0x18000
	s_mov_b32 s99, 0
	v_lshl_add_u64 v[158:159], s[98:99], 0, v[152:153]
	global_load_dwordx4 v[116:119], v[158:159], off offset:3584
	global_load_dwordx4 v[120:123], v[158:159], off offset:3648
	global_load_dwordx4 v[124:127], v[154:155], off offset:2064
	global_load_dwordx4 v[128:131], v[154:155], off offset:2048
	global_load_dwordx4 v[132:135], v[156:157], off offset:2064
	global_load_dwordx4 v[136:139], v[156:157], off offset:2048
	v_add_u32_e32 v63, s12, v63
	s_waitcnt vmcnt(17)
; #define LAS __attribute__((address_space(3)))
; __device__ __forceinline__ unsigned pk2(float lo, float hi) { unsigned r; asm("v_cvt_pk_bf16_f32 %0, %1, %2" : "=v"(r) : "v"(lo), "v"(hi)); return r; }
; __device__ __forceinline__ void rot8(u32x4 x1, u32x4 x2, const float* cs, const float* sn, float sc, u32x4& o1, u32x4& o2) {
;     const f32x4 c0 = *(const f32x4*)cs, c1 = *(const f32x4*)(cs + 4), s0 = *(const f32x4*)sn, s1 = *(const f32x4*)(sn + 4);
;     float a[8], b[8], c[8], s[8];
;     a[0] = bflo(x1.x); a[1] = bfhi(x1.x); a[2] = bflo(x1.y); a[3] = bfhi(x1.y); a[4] = bflo(x1.z); a[5] = bfhi(x1.z); a[6] = bflo(x1.w); a[7] = bfhi(x1.w);
;     b[0] = bflo(x2.x); b[1] = bfhi(x2.x); b[2] = bflo(x2.y); b[3] = bfhi(x2.y); b[4] = bflo(x2.z); b[5] = bfhi(x2.z); b[6] = bflo(x2.w); b[7] = bfhi(x2.w);
; #pragma unroll
;     for (int i = 0; i < 4; ++i) { c[i] = c0[i]; c[4 + i] = c1[i]; s[i] = s0[i]; s[4 + i] = s1[i]; }
;     float p[8], q[8];
; #pragma unroll
;     for (int i = 0; i < 8; ++i) { p[i] = (a[i] * c[i] - b[i] * s[i]) * sc; q[i] = (a[i] * s[i] + b[i] * c[i]) * sc; }
;     o1.x = pk2(p[0], p[1]); o1.y = pk2(p[2], p[3]); o1.z = pk2(p[4], p[5]); o1.w = pk2(p[6], p[7]);
;     o2.x = pk2(q[0], q[1]); o2.y = pk2(q[2], q[3]); o2.z = pk2(q[4], q[5]); o2.w = pk2(q[6], q[7]);
; __device__ __forceinline__ void retkv_item(const bf16_t* hbuf, const float* rot, float* kvbuf, LAS bf16_t* wl, int item, int lane) {
;     ...
;     { const int cr = lane >> 3, dc = lane & 7, fc = dc & 3;
; #pragma unroll
;       for (int i = 0; i < 8; ++i) { const int row = cr + 8 * i; const bf16_t* kp = hbuf + (t0 + row) * INWP + C_RK + h * 64;
;           const u32x4 x1 = *(const u32x4*)(kp + 8 * fc), x2 = *(const u32x4*)(kp + 32 + 8 * fc);
;           const int pos = n * 64 + row; u32x4 o1, o2;
;           rot8(x1, x2, rot + (size_t)pos * 32 + 8 * fc, rot + 16384 * 32 + (size_t)pos * 32 + 8 * fc, 0.125f, o1, o2);
;           const u32x4 w = dc < 4 ? o1 : o2;
;           LAS bf16_t* t = kT + (8 * dc) * TLD + row;
;           t[0 * TLD] = (bf16_t)(w.x & 0xffff); t[1 * TLD] = (bf16_t)(w.x >> 16); t[2 * TLD] = (bf16_t)(w.y & 0xffff); t[3 * TLD] = (bf16_t)(w.y >> 16);
;           t[4 * TLD] = (bf16_t)(w.z & 0xffff); t[5 * TLD] = (bf16_t)(w.z >> 16); t[6 * TLD] = (bf16_t)(w.w & 0xffff); t[7 * TLD] = (bf16_t)(w.w >> 16); } }
	v_lshlrev_b32_e32 v71, 16, v4
	s_waitcnt vmcnt(16)
	v_lshlrev_b32_e32 v70, 16, v8
	s_waitcnt vmcnt(14)
	v_mov_b32_e32 v73, v16
	s_waitcnt vmcnt(12)
	v_mov_b32_e32 v72, v66
	v_pk_mul_f32 v[72:73], v[72:73], v[70:71]
	s_nop 0
	v_sub_f32_e32 v1, v73, v72
	v_mov_b32_e32 v72, v16
	v_mov_b32_e32 v73, v66
	v_pk_mul_f32 v[70:71], v[72:73], v[70:71]
	v_mov_b32_e32 v66, v17
	v_add_f32_e32 v16, v70, v71
	v_mul_f32_e32 v51, 0x3e000000, v16
	v_and_b32_e32 v71, 0xffff0000, v4
	v_and_b32_e32 v70, 0xffff0000, v8
	v_mov_b32_e32 v16, v67
	v_pk_mul_f32 v[72:73], v[16:17], v[70:71]
	v_pk_mul_f32 v[16:17], v[66:67], v[70:71]
	v_sub_f32_e32 v4, v73, v72
	v_mul_f32_e32 v53, 0x3e000000, v4
	v_add_f32_e32 v4, v16, v17
	v_lshlrev_b32_e32 v17, 16, v5
	v_lshlrev_b32_e32 v16, 16, v9
	v_mov_b32_e32 v66, v68
	v_mov_b32_e32 v67, v18
	v_pk_mul_f32 v[66:67], v[66:67], v[16:17]
	v_mul_f32_e32 v55, 0x3e000000, v4
	v_sub_f32_e32 v4, v67, v66
	v_mov_b32_e32 v66, v18
	v_mov_b32_e32 v67, v68
	v_pk_mul_f32 v[16:17], v[66:67], v[16:17]
	v_mul_f32_e32 v57, 0x3e000000, v4
	v_add_f32_e32 v4, v16, v17
	v_mul_f32_e32 v16, 0x3e000000, v4
	v_and_b32_e32 v5, 0xffff0000, v5
	v_and_b32_e32 v4, 0xffff0000, v9
	v_mov_b32_e32 v18, v69
	v_mov_b32_e32 v68, v19
	v_pk_mul_f32 v[8:9], v[18:19], v[4:5]
	v_pk_mul_f32 v[4:5], v[68:69], v[4:5]
	v_sub_f32_e32 v8, v9, v8
	v_add_f32_e32 v4, v4, v5
	v_mul_f32_e32 v17, 0x3e000000, v8
	v_mul_f32_e32 v18, 0x3e000000, v4
	v_lshlrev_b32_e32 v5, 16, v6
	v_lshlrev_b32_e32 v4, 16, v10
	v_mov_b32_e32 v8, v20
	v_mov_b32_e32 v9, v12
	v_pk_mul_f32 v[8:9], v[8:9], v[4:5]
	v_mul_f32_e32 v1, 0x3e000000, v1
	v_sub_f32_e32 v8, v9, v8
	v_mul_f32_e32 v19, 0x3e000000, v8
	v_mov_b32_e32 v8, v12
	v_mov_b32_e32 v9, v20
	v_pk_mul_f32 v[4:5], v[8:9], v[4:5]
	v_mov_b32_e32 v12, v21
	v_add_f32_e32 v4, v4, v5
	v_mul_f32_e32 v59, 0x3e000000, v4
	v_and_b32_e32 v5, 0xffff0000, v6
	v_and_b32_e32 v4, 0xffff0000, v10
	v_mov_b32_e32 v20, v13
	v_pk_mul_f32 v[8:9], v[12:13], v[4:5]
	v_pk_mul_f32 v[4:5], v[20:21], v[4:5]
	v_sub_f32_e32 v6, v9, v8
	v_add_f32_e32 v4, v4, v5
	v_mul_f32_e32 v12, 0x3e000000, v4
	v_lshlrev_b32_e32 v5, 16, v7
	v_lshlrev_b32_e32 v4, 16, v11
	v_mov_b32_e32 v8, v22
	v_mov_b32_e32 v9, v14
	v_pk_mul_f32 v[8:9], v[8:9], v[4:5]
	v_mul_f32_e32 v10, 0x3e000000, v6
	v_sub_f32_e32 v6, v9, v8
	v_mov_b32_e32 v8, v14
	v_mov_b32_e32 v9, v22
	v_pk_mul_f32 v[4:5], v[8:9], v[4:5]
	v_mov_b32_e32 v14, v23
	v_add_f32_e32 v4, v4, v5
	v_mul_f32_e32 v8, 0x3e000000, v4
	v_and_b32_e32 v5, 0xffff0000, v7
	v_and_b32_e32 v4, 0xffff0000, v11
	v_mov_b32_e32 v22, v15
	v_mul_f32_e32 v13, 0x3e000000, v6
	v_pk_mul_f32 v[6:7], v[14:15], v[4:5]
	v_pk_mul_f32 v[4:5], v[22:23], v[4:5]
	v_sub_f32_e32 v6, v7, v6
	v_add_f32_e32 v4, v4, v5
	v_mul_f32_e32 v6, 0x3e000000, v6
	v_mul_f32_e32 v4, 0x3e000000, v4
	v_cvt_pk_bf16_f32 v1, v1, v53
	v_cvt_pk_bf16_f32 v5, v57, v17
	v_cvt_pk_bf16_f32 v6, v13, v6
	v_cvt_pk_bf16_f32 v9, v51, v55
	v_cvt_pk_bf16_f32 v4, v8, v4
	v_cvt_pk_bf16_f32 v7, v19, v10
	v_cvt_pk_bf16_f32 v10, v16, v18
	v_cvt_pk_bf16_f32 v11, v59, v12
	v_subrev_u32_e32 v12, 48, v0
	v_cndmask_b32_e32 v1, v9, v1, vcc
	v_cndmask_b32_e32 v4, v4, v6, vcc
	v_cndmask_b32_e32 v6, v11, v7, vcc
	v_cndmask_b32_e32 v5, v10, v5, vcc
	ds_write_b16 v29, v1
	ds_write_b16_d16_hi v29, v1 offset:144
	ds_write_b16 v29, v5 offset:288
	ds_write_b16_d16_hi v29, v5 offset:432
	ds_write_b16 v29, v6 offset:576
	ds_write_b16_d16_hi v29, v6 offset:720
	ds_write_b16 v29, v4 offset:864
	ds_write_b16_d16_hi v29, v4 offset:1008
	v_or_b32_e32 v1, s20, v26
	v_mad_u64_u32 v[4:5], s[0:1], v1, s5, v[2:3]
	v_mad_i32_i24 v5, s17, v207, v5
	v_ashrrev_i32_e32 v13, 31, v12
	v_lshl_add_u64 v[4:5], v[4:5], 0, s[38:39]
	v_lshlrev_b64 v[12:13], 7, v[12:13]
	v_lshl_add_u64 v[8:9], v[4:5], 0, v[60:61]
	v_lshl_add_u64 v[16:17], v[44:45], 0, v[12:13]
	v_lshl_add_u64 v[66:67], v[46:47], 0, v[12:13]
	s_waitcnt vmcnt(6)
	v_mov_b64_e32 v[4:5], v[92:93]
	v_mov_b64_e32 v[6:7], v[94:95]
	v_mov_b64_e32 v[8:9], v[96:97]
	v_mov_b64_e32 v[10:11], v[98:99]
	v_mov_b64_e32 v[12:13], v[100:101]
	v_mov_b64_e32 v[14:15], v[102:103]
	v_mov_b64_e32 v[16:17], v[104:105]
	v_mov_b64_e32 v[18:19], v[106:107]
	v_mov_b64_e32 v[20:21], v[108:109]
	v_mov_b64_e32 v[22:23], v[110:111]
	v_mov_b64_e32 v[66:67], v[112:113]
	v_mov_b64_e32 v[68:69], v[114:115]
	s_mov_b32 s98, 0x24000
	s_mov_b32 s99, 0
	v_lshl_add_u64 v[158:159], s[98:99], 0, v[152:153]
	global_load_dwordx4 v[92:95], v[158:159], off offset:3584
	global_load_dwordx4 v[96:99], v[158:159], off offset:3648
	global_load_dwordx4 v[100:103], v[154:155], off offset:3088
	global_load_dwordx4 v[104:107], v[154:155], off offset:3072
	global_load_dwordx4 v[108:111], v[156:157], off offset:3088
	global_load_dwordx4 v[112:115], v[156:157], off offset:3072
	v_lshlrev_b32_e32 v71, 16, v4
	v_lshlrev_b32_e32 v70, 16, v8
	v_mov_b32_e32 v72, v66
	v_mov_b32_e32 v73, v16
	v_pk_mul_f32 v[72:73], v[72:73], v[70:71]
	s_nop 0
	v_sub_f32_e32 v1, v73, v72
	v_mov_b32_e32 v72, v16
	v_mov_b32_e32 v73, v66
	v_pk_mul_f32 v[70:71], v[72:73], v[70:71]
	v_mov_b32_e32 v66, v17
	v_add_f32_e32 v16, v70, v71
	v_mul_f32_e32 v51, 0x3e000000, v16
	v_and_b32_e32 v71, 0xffff0000, v4
	v_and_b32_e32 v70, 0xffff0000, v8
	v_mov_b32_e32 v16, v67
	v_pk_mul_f32 v[72:73], v[16:17], v[70:71]
	v_pk_mul_f32 v[16:17], v[66:67], v[70:71]
	v_sub_f32_e32 v4, v73, v72
	v_mul_f32_e32 v53, 0x3e000000, v4
	v_add_f32_e32 v4, v16, v17
	v_lshlrev_b32_e32 v17, 16, v5
	v_lshlrev_b32_e32 v16, 16, v9
	v_mov_b32_e32 v66, v68
	v_mov_b32_e32 v67, v18
	v_pk_mul_f32 v[66:67], v[66:67], v[16:17]
	v_mul_f32_e32 v55, 0x3e000000, v4
	v_sub_f32_e32 v4, v67, v66
	v_mov_b32_e32 v66, v18
; #define LAS __attribute__((address_space(3)))
; __device__ __forceinline__ unsigned pk2(float lo, float hi) { unsigned r; asm("v_cvt_pk_bf16_f32 %0, %1, %2" : "=v"(r) : "v"(lo), "v"(hi)); return r; }
; __device__ __forceinline__ void rot8(u32x4 x1, u32x4 x2, const float* cs, const float* sn, float sc, u32x4& o1, u32x4& o2) {
;     const f32x4 c0 = *(const f32x4*)cs, c1 = *(const f32x4*)(cs + 4), s0 = *(const f32x4*)sn, s1 = *(const f32x4*)(sn + 4);
;     float a[8], b[8], c[8], s[8];
;     a[0] = bflo(x1.x); a[1] = bfhi(x1.x); a[2] = bflo(x1.y); a[3] = bfhi(x1.y); a[4] = bflo(x1.z); a[5] = bfhi(x1.z); a[6] = bflo(x1.w); a[7] = bfhi(x1.w);
;     b[0] = bflo(x2.x); b[1] = bfhi(x2.x); b[2] = bflo(x2.y); b[3] = bfhi(x2.y); b[4] = bflo(x2.z); b[5] = bfhi(x2.z); b[6] = bflo(x2.w); b[7] = bfhi(x2.w);
; #pragma unroll
;     for (int i = 0; i < 4; ++i) { c[i] = c0[i]; c[4 + i] = c1[i]; s[i] = s0[i]; s[4 + i] = s1[i]; }
;     float p[8], q[8];
; #pragma unroll
;     for (int i = 0; i < 8; ++i) { p[i] = (a[i] * c[i] - b[i] * s[i]) * sc; q[i] = (a[i] * s[i] + b[i] * c[i]) * sc; }
;     o1.x = pk2(p[0], p[1]); o1.y = pk2(p[2], p[3]); o1.z = pk2(p[4], p[5]); o1.w = pk2(p[6], p[7]);
;     o2.x = pk2(q[0], q[1]); o2.y = pk2(q[2], q[3]); o2.z = pk2(q[4], q[5]); o2.w = pk2(q[6], q[7]);
; __device__ __forceinline__ void retkv_item(const bf16_t* hbuf, const float* rot, float* kvbuf, LAS bf16_t* wl, int item, int lane) {
;     ...
;     { const int cr = lane >> 3, dc = lane & 7, fc = dc & 3;
; #pragma unroll
;       for (int i = 0; i < 8; ++i) { const int row = cr + 8 * i; const bf16_t* kp = hbuf + (t0 + row) * INWP + C_RK + h * 64;
;           const u32x4 x1 = *(const u32x4*)(kp + 8 * fc), x2 = *(const u32x4*)(kp + 32 + 8 * fc);
;           const int pos = n * 64 + row; u32x4 o1, o2;
;           rot8(x1, x2, rot + (size_t)pos * 32 + 8 * fc, rot + 16384 * 32 + (size_t)pos * 32 + 8 * fc, 0.125f, o1, o2);
;           const u32x4 w = dc < 4 ? o1 : o2;
;           LAS bf16_t* t = kT + (8 * dc) * TLD + row;
;           t[0 * TLD] = (bf16_t)(w.x & 0xffff); t[1 * TLD] = (bf16_t)(w.x >> 16); t[2 * TLD] = (bf16_t)(w.y & 0xffff); t[3 * TLD] = (bf16_t)(w.y >> 16);
;           t[4 * TLD] = (bf16_t)(w.z & 0xffff); t[5 * TLD] = (bf16_t)(w.z >> 16); t[6 * TLD] = (bf16_t)(w.w & 0xffff); t[7 * TLD] = (bf16_t)(w.w >> 16); } }
	v_mov_b32_e32 v67, v68
	v_pk_mul_f32 v[16:17], v[66:67], v[16:17]
	v_mul_f32_e32 v57, 0x3e000000, v4
	v_add_f32_e32 v4, v16, v17
	v_mul_f32_e32 v16, 0x3e000000, v4
	v_and_b32_e32 v5, 0xffff0000, v5
	v_and_b32_e32 v4, 0xffff0000, v9
	v_mov_b32_e32 v18, v69
	v_mov_b32_e32 v68, v19
	v_pk_mul_f32 v[8:9], v[18:19], v[4:5]
	v_pk_mul_f32 v[4:5], v[68:69], v[4:5]
	v_sub_f32_e32 v8, v9, v8
	v_add_f32_e32 v4, v4, v5
	v_mul_f32_e32 v17, 0x3e000000, v8
	v_mul_f32_e32 v18, 0x3e000000, v4
	v_lshlrev_b32_e32 v5, 16, v6
	v_lshlrev_b32_e32 v4, 16, v10
	v_mov_b32_e32 v8, v20
	v_mov_b32_e32 v9, v12
	v_pk_mul_f32 v[8:9], v[8:9], v[4:5]
	v_mul_f32_e32 v1, 0x3e000000, v1
	v_sub_f32_e32 v8, v9, v8
	v_mul_f32_e32 v19, 0x3e000000, v8
	v_mov_b32_e32 v8, v12
	v_mov_b32_e32 v9, v20
	v_pk_mul_f32 v[4:5], v[8:9], v[4:5]
	v_mov_b32_e32 v12, v21
	v_add_f32_e32 v4, v4, v5
	v_mul_f32_e32 v59, 0x3e000000, v4
	v_and_b32_e32 v5, 0xffff0000, v6
	v_and_b32_e32 v4, 0xffff0000, v10
	v_mov_b32_e32 v20, v13
	v_pk_mul_f32 v[8:9], v[12:13], v[4:5]
	v_pk_mul_f32 v[4:5], v[20:21], v[4:5]
	v_sub_f32_e32 v6, v9, v8
	v_add_f32_e32 v4, v4, v5
	v_mul_f32_e32 v12, 0x3e000000, v4
	v_lshlrev_b32_e32 v5, 16, v7
	v_lshlrev_b32_e32 v4, 16, v11
	v_mov_b32_e32 v8, v22
	v_mov_b32_e32 v9, v14
	v_pk_mul_f32 v[8:9], v[8:9], v[4:5]
	v_mul_f32_e32 v10, 0x3e000000, v6
	v_sub_f32_e32 v6, v9, v8
	v_mov_b32_e32 v8, v14
	v_mov_b32_e32 v9, v22
	v_pk_mul_f32 v[4:5], v[8:9], v[4:5]
	v_mov_b32_e32 v14, v23
	v_add_f32_e32 v4, v4, v5
	v_mul_f32_e32 v8, 0x3e000000, v4
	v_and_b32_e32 v5, 0xffff0000, v7
	v_and_b32_e32 v4, 0xffff0000, v11
	v_mov_b32_e32 v22, v15
	v_mul_f32_e32 v13, 0x3e000000, v6
	v_pk_mul_f32 v[6:7], v[14:15], v[4:5]
	v_pk_mul_f32 v[4:5], v[22:23], v[4:5]
	v_sub_f32_e32 v6, v7, v6
	v_add_f32_e32 v4, v4, v5
	v_mul_f32_e32 v6, 0x3e000000, v6
	v_mul_f32_e32 v4, 0x3e000000, v4
	v_cvt_pk_bf16_f32 v1, v1, v53
	v_cvt_pk_bf16_f32 v5, v57, v17
	v_cvt_pk_bf16_f32 v6, v13, v6
	v_cvt_pk_bf16_f32 v9, v51, v55
	v_cvt_pk_bf16_f32 v4, v8, v4
	v_cvt_pk_bf16_f32 v7, v19, v10
	v_cvt_pk_bf16_f32 v10, v16, v18
	v_cvt_pk_bf16_f32 v11, v59, v12
	v_subrev_u32_e32 v12, 40, v0
	v_cndmask_b32_e32 v1, v9, v1, vcc
	v_cndmask_b32_e32 v4, v4, v6, vcc
	v_cndmask_b32_e32 v6, v11, v7, vcc
	v_cndmask_b32_e32 v5, v10, v5, vcc
	ds_write_b16 v29, v1 offset:16
	ds_write_b16_d16_hi v29, v1 offset:160
	ds_write_b16 v29, v5 offset:304
	ds_write_b16_d16_hi v29, v5 offset:448
	ds_write_b16 v29, v6 offset:592
	ds_write_b16_d16_hi v29, v6 offset:736
	ds_write_b16 v29, v4 offset:880
	ds_write_b16_d16_hi v29, v4 offset:1024
	v_or_b32_e32 v1, s20, v28
	v_mad_u64_u32 v[4:5], s[0:1], v1, s5, v[2:3]
	v_mad_i32_i24 v5, s17, v207, v5
	v_ashrrev_i32_e32 v13, 31, v12
	v_lshl_add_u64 v[4:5], v[4:5], 0, s[38:39]
	v_lshlrev_b64 v[12:13], 7, v[12:13]
	v_lshl_add_u64 v[8:9], v[4:5], 0, v[60:61]
	v_lshl_add_u64 v[16:17], v[44:45], 0, v[12:13]
	v_lshl_add_u64 v[66:67], v[46:47], 0, v[12:13]
	s_waitcnt vmcnt(6)
	v_mov_b64_e32 v[4:5], v[116:117]
	v_mov_b64_e32 v[6:7], v[118:119]
	v_mov_b64_e32 v[8:9], v[120:121]
	v_mov_b64_e32 v[10:11], v[122:123]
	v_mov_b64_e32 v[12:13], v[124:125]
	v_mov_b64_e32 v[14:15], v[126:127]
	v_mov_b64_e32 v[16:17], v[128:129]
	v_mov_b64_e32 v[18:19], v[130:131]
	v_mov_b64_e32 v[20:21], v[132:133]
	v_mov_b64_e32 v[22:23], v[134:135]
	v_mov_b64_e32 v[66:67], v[136:137]
	v_mov_b64_e32 v[68:69], v[138:139]
	s_mov_b32 s98, 0x30000
	s_mov_b32 s99, 0
	v_lshl_add_u64 v[158:159], s[98:99], 0, v[152:153]
	global_load_dwordx4 v[116:119], v[158:159], off offset:3584
	global_load_dwordx4 v[120:123], v[158:159], off offset:3648
	s_mov_b32 s98, 0x1000
	v_lshl_add_u64 v[158:159], s[98:99], 0, v[154:155]
	global_load_dwordx4 v[124:127], v[158:159], off offset:16
	global_load_dwordx4 v[128:131], v[158:159], off
	v_lshl_add_u64 v[158:159], s[98:99], 0, v[156:157]
	global_load_dwordx4 v[132:135], v[158:159], off offset:16
	global_load_dwordx4 v[136:139], v[158:159], off
	v_lshlrev_b32_e32 v71, 16, v4
	v_lshlrev_b32_e32 v70, 16, v8
	v_mov_b32_e32 v72, v66
	v_mov_b32_e32 v73, v16
	v_pk_mul_f32 v[72:73], v[72:73], v[70:71]
	s_nop 0
	v_sub_f32_e32 v1, v73, v72
	v_mov_b32_e32 v72, v16
	v_mov_b32_e32 v73, v66
	v_pk_mul_f32 v[70:71], v[72:73], v[70:71]
	v_mov_b32_e32 v66, v17
	v_add_f32_e32 v16, v70, v71
	v_mul_f32_e32 v51, 0x3e000000, v16
	v_and_b32_e32 v71, 0xffff0000, v4
	v_and_b32_e32 v70, 0xffff0000, v8
	v_mov_b32_e32 v16, v67
	v_pk_mul_f32 v[72:73], v[16:17], v[70:71]
	v_pk_mul_f32 v[16:17], v[66:67], v[70:71]
	v_sub_f32_e32 v4, v73, v72
	v_mul_f32_e32 v53, 0x3e000000, v4
	v_add_f32_e32 v4, v16, v17
	v_lshlrev_b32_e32 v17, 16, v5
	v_lshlrev_b32_e32 v16, 16, v9
	v_mov_b32_e32 v66, v68
	v_mov_b32_e32 v67, v18
	v_pk_mul_f32 v[66:67], v[66:67], v[16:17]
	v_mul_f32_e32 v55, 0x3e000000, v4
	v_sub_f32_e32 v4, v67, v66
	v_mov_b32_e32 v66, v18
	v_mov_b32_e32 v67, v68
	v_pk_mul_f32 v[16:17], v[66:67], v[16:17]
	v_mul_f32_e32 v57, 0x3e000000, v4
	v_add_f32_e32 v4, v16, v17
	v_mul_f32_e32 v16, 0x3e000000, v4
	v_and_b32_e32 v5, 0xffff0000, v5
	v_and_b32_e32 v4, 0xffff0000, v9
	v_mov_b32_e32 v18, v69
	v_mov_b32_e32 v68, v19
	v_pk_mul_f32 v[8:9], v[18:19], v[4:5]
	v_pk_mul_f32 v[4:5], v[68:69], v[4:5]
	v_sub_f32_e32 v8, v9, v8
	v_add_f32_e32 v4, v4, v5
	v_mul_f32_e32 v17, 0x3e000000, v8
	v_mul_f32_e32 v18, 0x3e000000, v4
	v_lshlrev_b32_e32 v5, 16, v6
	v_lshlrev_b32_e32 v4, 16, v10
	v_mov_b32_e32 v8, v20
	v_mov_b32_e32 v9, v12
	v_pk_mul_f32 v[8:9], v[8:9], v[4:5]
	v_mul_f32_e32 v1, 0x3e000000, v1
	v_sub_f32_e32 v8, v9, v8
	v_mul_f32_e32 v19, 0x3e000000, v8
	v_mov_b32_e32 v8, v12
	v_mov_b32_e32 v9, v20
	v_pk_mul_f32 v[4:5], v[8:9], v[4:5]
	v_mov_b32_e32 v12, v21
; #define LAS __attribute__((address_space(3)))
; __device__ __forceinline__ unsigned pk2(float lo, float hi) { unsigned r; asm("v_cvt_pk_bf16_f32 %0, %1, %2" : "=v"(r) : "v"(lo), "v"(hi)); return r; }
; __device__ __forceinline__ void rot8(u32x4 x1, u32x4 x2, const float* cs, const float* sn, float sc, u32x4& o1, u32x4& o2) {
;     const f32x4 c0 = *(const f32x4*)cs, c1 = *(const f32x4*)(cs + 4), s0 = *(const f32x4*)sn, s1 = *(const f32x4*)(sn + 4);
;     float a[8], b[8], c[8], s[8];
;     a[0] = bflo(x1.x); a[1] = bfhi(x1.x); a[2] = bflo(x1.y); a[3] = bfhi(x1.y); a[4] = bflo(x1.z); a[5] = bfhi(x1.z); a[6] = bflo(x1.w); a[7] = bfhi(x1.w);
;     b[0] = bflo(x2.x); b[1] = bfhi(x2.x); b[2] = bflo(x2.y); b[3] = bfhi(x2.y); b[4] = bflo(x2.z); b[5] = bfhi(x2.z); b[6] = bflo(x2.w); b[7] = bfhi(x2.w);
; #pragma unroll
;     for (int i = 0; i < 4; ++i) { c[i] = c0[i]; c[4 + i] = c1[i]; s[i] = s0[i]; s[4 + i] = s1[i]; }
;     float p[8], q[8];
; #pragma unroll
;     for (int i = 0; i < 8; ++i) { p[i] = (a[i] * c[i] - b[i] * s[i]) * sc; q[i] = (a[i] * s[i] + b[i] * c[i]) * sc; }
;     o1.x = pk2(p[0], p[1]); o1.y = pk2(p[2], p[3]); o1.z = pk2(p[4], p[5]); o1.w = pk2(p[6], p[7]);
;     o2.x = pk2(q[0], q[1]); o2.y = pk2(q[2], q[3]); o2.z = pk2(q[4], q[5]); o2.w = pk2(q[6], q[7]);
; __device__ __forceinline__ void retkv_item(const bf16_t* hbuf, const float* rot, float* kvbuf, LAS bf16_t* wl, int item, int lane) {
;     ...
;     { const int cr = lane >> 3, dc = lane & 7, fc = dc & 3;
; #pragma unroll
;       for (int i = 0; i < 8; ++i) { const int row = cr + 8 * i; const bf16_t* kp = hbuf + (t0 + row) * INWP + C_RK + h * 64;
;           const u32x4 x1 = *(const u32x4*)(kp + 8 * fc), x2 = *(const u32x4*)(kp + 32 + 8 * fc);
;           const int pos = n * 64 + row; u32x4 o1, o2;
;           rot8(x1, x2, rot + (size_t)pos * 32 + 8 * fc, rot + 16384 * 32 + (size_t)pos * 32 + 8 * fc, 0.125f, o1, o2);
;           const u32x4 w = dc < 4 ? o1 : o2;
;           LAS bf16_t* t = kT + (8 * dc) * TLD + row;
;           t[0 * TLD] = (bf16_t)(w.x & 0xffff); t[1 * TLD] = (bf16_t)(w.x >> 16); t[2 * TLD] = (bf16_t)(w.y & 0xffff); t[3 * TLD] = (bf16_t)(w.y >> 16);
;           t[4 * TLD] = (bf16_t)(w.z & 0xffff); t[5 * TLD] = (bf16_t)(w.z >> 16); t[6 * TLD] = (bf16_t)(w.w & 0xffff); t[7 * TLD] = (bf16_t)(w.w >> 16); } }
	v_add_f32_e32 v4, v4, v5
	v_mul_f32_e32 v59, 0x3e000000, v4
	v_and_b32_e32 v5, 0xffff0000, v6
	v_and_b32_e32 v4, 0xffff0000, v10
	v_mov_b32_e32 v20, v13
	v_pk_mul_f32 v[8:9], v[12:13], v[4:5]
	v_pk_mul_f32 v[4:5], v[20:21], v[4:5]
	v_sub_f32_e32 v6, v9, v8
	v_add_f32_e32 v4, v4, v5
	v_mul_f32_e32 v12, 0x3e000000, v4
	v_lshlrev_b32_e32 v5, 16, v7
	v_lshlrev_b32_e32 v4, 16, v11
	v_mov_b32_e32 v8, v22
	v_mov_b32_e32 v9, v14
	v_pk_mul_f32 v[8:9], v[8:9], v[4:5]
	v_mul_f32_e32 v10, 0x3e000000, v6
	v_sub_f32_e32 v6, v9, v8
	v_mov_b32_e32 v8, v14
	v_mov_b32_e32 v9, v22
	v_pk_mul_f32 v[4:5], v[8:9], v[4:5]
	v_mov_b32_e32 v14, v23
	v_add_f32_e32 v4, v4, v5
	v_mul_f32_e32 v8, 0x3e000000, v4
	v_and_b32_e32 v5, 0xffff0000, v7
	v_and_b32_e32 v4, 0xffff0000, v11
	v_mov_b32_e32 v22, v15
	v_mul_f32_e32 v13, 0x3e000000, v6
	v_pk_mul_f32 v[6:7], v[14:15], v[4:5]
	v_pk_mul_f32 v[4:5], v[22:23], v[4:5]
	v_sub_f32_e32 v6, v7, v6
	v_add_f32_e32 v4, v4, v5
	v_mul_f32_e32 v6, 0x3e000000, v6
	v_mul_f32_e32 v4, 0x3e000000, v4
	v_cvt_pk_bf16_f32 v1, v1, v53
	v_cvt_pk_bf16_f32 v5, v57, v17
	v_cvt_pk_bf16_f32 v6, v13, v6
	v_cvt_pk_bf16_f32 v9, v51, v55
	v_cvt_pk_bf16_f32 v4, v8, v4
	v_cvt_pk_bf16_f32 v7, v19, v10
	v_cvt_pk_bf16_f32 v10, v16, v18
	v_cvt_pk_bf16_f32 v11, v59, v12
	v_subrev_u32_e32 v12, 32, v0
	v_cndmask_b32_e32 v1, v9, v1, vcc
	v_cndmask_b32_e32 v4, v4, v6, vcc
	v_cndmask_b32_e32 v6, v11, v7, vcc
	v_cndmask_b32_e32 v5, v10, v5, vcc
	ds_write_b16 v29, v1 offset:32
	ds_write_b16_d16_hi v29, v1 offset:176
	ds_write_b16 v29, v5 offset:320
	ds_write_b16_d16_hi v29, v5 offset:464
	ds_write_b16 v29, v6 offset:608
	ds_write_b16_d16_hi v29, v6 offset:752
	ds_write_b16 v29, v4 offset:896
	ds_write_b16_d16_hi v29, v4 offset:1040
	v_or_b32_e32 v1, s20, v30
	v_mad_u64_u32 v[4:5], s[0:1], v1, s5, v[2:3]
	v_mad_i32_i24 v5, s17, v207, v5
	v_ashrrev_i32_e32 v13, 31, v12
	v_lshl_add_u64 v[4:5], v[4:5], 0, s[38:39]
	v_lshlrev_b64 v[12:13], 7, v[12:13]
	v_lshl_add_u64 v[8:9], v[4:5], 0, v[60:61]
	v_lshl_add_u64 v[16:17], v[44:45], 0, v[12:13]
	v_lshl_add_u64 v[66:67], v[46:47], 0, v[12:13]
	s_waitcnt vmcnt(6)
	v_mov_b64_e32 v[4:5], v[92:93]
	v_mov_b64_e32 v[6:7], v[94:95]
	v_mov_b64_e32 v[8:9], v[96:97]
	v_mov_b64_e32 v[10:11], v[98:99]
	v_mov_b64_e32 v[12:13], v[100:101]
	v_mov_b64_e32 v[14:15], v[102:103]
	v_mov_b64_e32 v[16:17], v[104:105]
	v_mov_b64_e32 v[18:19], v[106:107]
	v_mov_b64_e32 v[20:21], v[108:109]
	v_mov_b64_e32 v[22:23], v[110:111]
	v_mov_b64_e32 v[66:67], v[112:113]
	v_mov_b64_e32 v[68:69], v[114:115]
	s_mov_b32 s98, 0x3c000
	s_mov_b32 s99, 0
	v_lshl_add_u64 v[158:159], s[98:99], 0, v[152:153]
	global_load_dwordx4 v[92:95], v[158:159], off offset:3584
	global_load_dwordx4 v[96:99], v[158:159], off offset:3648
	s_mov_b32 s98, 0x1400
	v_lshl_add_u64 v[158:159], s[98:99], 0, v[154:155]
	global_load_dwordx4 v[100:103], v[158:159], off offset:16
	global_load_dwordx4 v[104:107], v[158:159], off
	v_lshl_add_u64 v[158:159], s[98:99], 0, v[156:157]
	global_load_dwordx4 v[108:111], v[158:159], off offset:16
	global_load_dwordx4 v[112:115], v[158:159], off
	v_lshlrev_b32_e32 v71, 16, v4
	v_lshlrev_b32_e32 v70, 16, v8
	v_mov_b32_e32 v72, v66
	v_mov_b32_e32 v73, v16
	v_pk_mul_f32 v[72:73], v[72:73], v[70:71]
	s_nop 0
	v_sub_f32_e32 v1, v73, v72
	v_mov_b32_e32 v72, v16
	v_mov_b32_e32 v73, v66
	v_pk_mul_f32 v[70:71], v[72:73], v[70:71]
	v_mov_b32_e32 v66, v17
	v_add_f32_e32 v16, v70, v71
	v_mul_f32_e32 v51, 0x3e000000, v16
	v_and_b32_e32 v71, 0xffff0000, v4
	v_and_b32_e32 v70, 0xffff0000, v8
	v_mov_b32_e32 v16, v67
	v_pk_mul_f32 v[72:73], v[16:17], v[70:71]
	v_pk_mul_f32 v[16:17], v[66:67], v[70:71]
	v_sub_f32_e32 v4, v73, v72
	v_mul_f32_e32 v53, 0x3e000000, v4
	v_add_f32_e32 v4, v16, v17
	v_lshlrev_b32_e32 v17, 16, v5
	v_lshlrev_b32_e32 v16, 16, v9
	v_mov_b32_e32 v66, v68
	v_mov_b32_e32 v67, v18
	v_pk_mul_f32 v[66:67], v[66:67], v[16:17]
	v_mul_f32_e32 v55, 0x3e000000, v4
	v_sub_f32_e32 v4, v67, v66
	v_mov_b32_e32 v66, v18
	v_mov_b32_e32 v67, v68
	v_pk_mul_f32 v[16:17], v[66:67], v[16:17]
	v_mul_f32_e32 v57, 0x3e000000, v4
	v_add_f32_e32 v4, v16, v17
	v_mul_f32_e32 v16, 0x3e000000, v4
	v_and_b32_e32 v5, 0xffff0000, v5
	v_and_b32_e32 v4, 0xffff0000, v9
	v_mov_b32_e32 v18, v69
	v_mov_b32_e32 v68, v19
	v_pk_mul_f32 v[8:9], v[18:19], v[4:5]
	v_pk_mul_f32 v[4:5], v[68:69], v[4:5]
	v_sub_f32_e32 v8, v9, v8
	v_add_f32_e32 v4, v4, v5
	v_mul_f32_e32 v17, 0x3e000000, v8
	v_mul_f32_e32 v18, 0x3e000000, v4
	v_lshlrev_b32_e32 v5, 16, v6
	v_lshlrev_b32_e32 v4, 16, v10
	v_mov_b32_e32 v8, v20
	v_mov_b32_e32 v9, v12
	v_pk_mul_f32 v[8:9], v[8:9], v[4:5]
	v_mul_f32_e32 v1, 0x3e000000, v1
	v_sub_f32_e32 v8, v9, v8
	v_mul_f32_e32 v19, 0x3e000000, v8
	v_mov_b32_e32 v8, v12
	v_mov_b32_e32 v9, v20
	v_pk_mul_f32 v[4:5], v[8:9], v[4:5]
	v_mov_b32_e32 v12, v21
	v_add_f32_e32 v4, v4, v5
	v_mul_f32_e32 v59, 0x3e000000, v4
	v_and_b32_e32 v5, 0xffff0000, v6
	v_and_b32_e32 v4, 0xffff0000, v10
	v_mov_b32_e32 v20, v13
	v_pk_mul_f32 v[8:9], v[12:13], v[4:5]
	v_pk_mul_f32 v[4:5], v[20:21], v[4:5]
	v_sub_f32_e32 v6, v9, v8
	v_add_f32_e32 v4, v4, v5
	v_mul_f32_e32 v12, 0x3e000000, v4
	v_lshlrev_b32_e32 v5, 16, v7
	v_lshlrev_b32_e32 v4, 16, v11
	v_mov_b32_e32 v8, v22
	v_mov_b32_e32 v9, v14
	v_pk_mul_f32 v[8:9], v[8:9], v[4:5]
	v_mul_f32_e32 v10, 0x3e000000, v6
	v_sub_f32_e32 v6, v9, v8
	v_mov_b32_e32 v8, v14
	v_mov_b32_e32 v9, v22
	v_pk_mul_f32 v[4:5], v[8:9], v[4:5]
	v_mov_b32_e32 v14, v23
	v_add_f32_e32 v4, v4, v5
	v_mul_f32_e32 v8, 0x3e000000, v4
	v_and_b32_e32 v5, 0xffff0000, v7
	v_and_b32_e32 v4, 0xffff0000, v11
	v_mov_b32_e32 v22, v15
	v_mul_f32_e32 v13, 0x3e000000, v6
	v_pk_mul_f32 v[6:7], v[14:15], v[4:5]
	v_pk_mul_f32 v[4:5], v[22:23], v[4:5]
	v_sub_f32_e32 v6, v7, v6
	v_add_f32_e32 v4, v4, v5
	v_mul_f32_e32 v6, 0x3e000000, v6
	v_mul_f32_e32 v4, 0x3e000000, v4
	v_cvt_pk_bf16_f32 v1, v1, v53
	v_cvt_pk_bf16_f32 v5, v57, v17
	v_cvt_pk_bf16_f32 v6, v13, v6
	v_cvt_pk_bf16_f32 v9, v51, v55
	v_cvt_pk_bf16_f32 v4, v8, v4
	v_cvt_pk_bf16_f32 v7, v19, v10
	v_cvt_pk_bf16_f32 v10, v16, v18
	v_cvt_pk_bf16_f32 v11, v59, v12
	v_subrev_u32_e32 v12, 24, v0
	v_cndmask_b32_e32 v1, v9, v1, vcc
	v_cndmask_b32_e32 v4, v4, v6, vcc
	v_cndmask_b32_e32 v6, v11, v7, vcc
	v_cndmask_b32_e32 v5, v10, v5, vcc
	ds_write_b16 v29, v1 offset:48
	ds_write_b16_d16_hi v29, v1 offset:192
	ds_write_b16 v29, v5 offset:336
	ds_write_b16_d16_hi v29, v5 offset:480
	ds_write_b16 v29, v6 offset:624
	ds_write_b16_d16_hi v29, v6 offset:768
	ds_write_b16 v29, v4 offset:912
	ds_write_b16_d16_hi v29, v4 offset:1056
	v_or_b32_e32 v1, s20, v34
	v_mad_u64_u32 v[4:5], s[0:1], v1, s5, v[2:3]
	v_mad_i32_i24 v5, s17, v207, v5
	v_ashrrev_i32_e32 v13, 31, v12
	v_lshl_add_u64 v[4:5], v[4:5], 0, s[38:39]
	v_lshlrev_b64 v[12:13], 7, v[12:13]
	v_lshl_add_u64 v[8:9], v[4:5], 0, v[60:61]
	v_lshl_add_u64 v[16:17], v[44:45], 0, v[12:13]
	v_lshl_add_u64 v[66:67], v[46:47], 0, v[12:13]
	s_waitcnt vmcnt(6)
; #define LAS __attribute__((address_space(3)))
; __device__ __forceinline__ unsigned pk2(float lo, float hi) { unsigned r; asm("v_cvt_pk_bf16_f32 %0, %1, %2" : "=v"(r) : "v"(lo), "v"(hi)); return r; }
; __device__ __forceinline__ void rot8(u32x4 x1, u32x4 x2, const float* cs, const float* sn, float sc, u32x4& o1, u32x4& o2) {
;     const f32x4 c0 = *(const f32x4*)cs, c1 = *(const f32x4*)(cs + 4), s0 = *(const f32x4*)sn, s1 = *(const f32x4*)(sn + 4);
;     float a[8], b[8], c[8], s[8];
;     a[0] = bflo(x1.x); a[1] = bfhi(x1.x); a[2] = bflo(x1.y); a[3] = bfhi(x1.y); a[4] = bflo(x1.z); a[5] = bfhi(x1.z); a[6] = bflo(x1.w); a[7] = bfhi(x1.w);
;     b[0] = bflo(x2.x); b[1] = bfhi(x2.x); b[2] = bflo(x2.y); b[3] = bfhi(x2.y); b[4] = bflo(x2.z); b[5] = bfhi(x2.z); b[6] = bflo(x2.w); b[7] = bfhi(x2.w);
; #pragma unroll
;     for (int i = 0; i < 4; ++i) { c[i] = c0[i]; c[4 + i] = c1[i]; s[i] = s0[i]; s[4 + i] = s1[i]; }
;     float p[8], q[8];
; #pragma unroll
;     for (int i = 0; i < 8; ++i) { p[i] = (a[i] * c[i] - b[i] * s[i]) * sc; q[i] = (a[i] * s[i] + b[i] * c[i]) * sc; }
;     o1.x = pk2(p[0], p[1]); o1.y = pk2(p[2], p[3]); o1.z = pk2(p[4], p[5]); o1.w = pk2(p[6], p[7]);
;     o2.x = pk2(q[0], q[1]); o2.y = pk2(q[2], q[3]); o2.z = pk2(q[4], q[5]); o2.w = pk2(q[6], q[7]);
; __device__ __forceinline__ void retkv_item(const bf16_t* hbuf, const float* rot, float* kvbuf, LAS bf16_t* wl, int item, int lane) {
;     ...
;     { const int cr = lane >> 3, dc = lane & 7, fc = dc & 3;
; #pragma unroll
;       for (int i = 0; i < 8; ++i) { const int row = cr + 8 * i; const bf16_t* kp = hbuf + (t0 + row) * INWP + C_RK + h * 64;
;           const u32x4 x1 = *(const u32x4*)(kp + 8 * fc), x2 = *(const u32x4*)(kp + 32 + 8 * fc);
;           const int pos = n * 64 + row; u32x4 o1, o2;
;           rot8(x1, x2, rot + (size_t)pos * 32 + 8 * fc, rot + 16384 * 32 + (size_t)pos * 32 + 8 * fc, 0.125f, o1, o2);
;           const u32x4 w = dc < 4 ? o1 : o2;
;           LAS bf16_t* t = kT + (8 * dc) * TLD + row;
;           t[0 * TLD] = (bf16_t)(w.x & 0xffff); t[1 * TLD] = (bf16_t)(w.x >> 16); t[2 * TLD] = (bf16_t)(w.y & 0xffff); t[3 * TLD] = (bf16_t)(w.y >> 16);
;           t[4 * TLD] = (bf16_t)(w.z & 0xffff); t[5 * TLD] = (bf16_t)(w.z >> 16); t[6 * TLD] = (bf16_t)(w.w & 0xffff); t[7 * TLD] = (bf16_t)(w.w >> 16); } }
	v_mov_b64_e32 v[4:5], v[116:117]
	v_mov_b64_e32 v[6:7], v[118:119]
	v_mov_b64_e32 v[8:9], v[120:121]
	v_mov_b64_e32 v[10:11], v[122:123]
	v_mov_b64_e32 v[12:13], v[124:125]
	v_mov_b64_e32 v[14:15], v[126:127]
	v_mov_b64_e32 v[16:17], v[128:129]
	v_mov_b64_e32 v[18:19], v[130:131]
	v_mov_b64_e32 v[20:21], v[132:133]
	v_mov_b64_e32 v[22:23], v[134:135]
	v_mov_b64_e32 v[66:67], v[136:137]
	v_mov_b64_e32 v[68:69], v[138:139]
	s_mov_b32 s98, 0x48000
	s_mov_b32 s99, 0
	v_lshl_add_u64 v[158:159], s[98:99], 0, v[152:153]
	global_load_dwordx4 v[116:119], v[158:159], off offset:3584
	global_load_dwordx4 v[120:123], v[158:159], off offset:3648
	s_mov_b32 s98, 0x1800
	v_lshl_add_u64 v[158:159], s[98:99], 0, v[154:155]
	global_load_dwordx4 v[124:127], v[158:159], off offset:16
	global_load_dwordx4 v[128:131], v[158:159], off
	v_lshl_add_u64 v[158:159], s[98:99], 0, v[156:157]
	global_load_dwordx4 v[132:135], v[158:159], off offset:16
	global_load_dwordx4 v[136:139], v[158:159], off
	v_lshlrev_b32_e32 v71, 16, v4
	v_lshlrev_b32_e32 v70, 16, v8
	v_mov_b32_e32 v72, v66
	v_mov_b32_e32 v73, v16
	v_pk_mul_f32 v[72:73], v[72:73], v[70:71]
	s_nop 0
	v_sub_f32_e32 v1, v73, v72
	v_mov_b32_e32 v72, v16
	v_mov_b32_e32 v73, v66
	v_pk_mul_f32 v[70:71], v[72:73], v[70:71]
	v_mov_b32_e32 v66, v17
	v_add_f32_e32 v16, v70, v71
	v_mul_f32_e32 v51, 0x3e000000, v16
	v_and_b32_e32 v71, 0xffff0000, v4
	v_and_b32_e32 v70, 0xffff0000, v8
	v_mov_b32_e32 v16, v67
	v_pk_mul_f32 v[72:73], v[16:17], v[70:71]
	v_pk_mul_f32 v[16:17], v[66:67], v[70:71]
	v_sub_f32_e32 v4, v73, v72
	v_mul_f32_e32 v53, 0x3e000000, v4
	v_add_f32_e32 v4, v16, v17
	v_lshlrev_b32_e32 v17, 16, v5
	v_lshlrev_b32_e32 v16, 16, v9
	v_mov_b32_e32 v66, v68
	v_mov_b32_e32 v67, v18
	v_pk_mul_f32 v[66:67], v[66:67], v[16:17]
	v_mul_f32_e32 v55, 0x3e000000, v4
	v_sub_f32_e32 v4, v67, v66
	v_mov_b32_e32 v66, v18
	v_mov_b32_e32 v67, v68
	v_pk_mul_f32 v[16:17], v[66:67], v[16:17]
	v_mul_f32_e32 v57, 0x3e000000, v4
	v_add_f32_e32 v4, v16, v17
	v_mul_f32_e32 v16, 0x3e000000, v4
	v_and_b32_e32 v5, 0xffff0000, v5
	v_and_b32_e32 v4, 0xffff0000, v9
	v_mov_b32_e32 v18, v69
	v_mov_b32_e32 v68, v19
	v_pk_mul_f32 v[8:9], v[18:19], v[4:5]
	v_pk_mul_f32 v[4:5], v[68:69], v[4:5]
	v_sub_f32_e32 v8, v9, v8
	v_add_f32_e32 v4, v4, v5
	v_mul_f32_e32 v17, 0x3e000000, v8
	v_mul_f32_e32 v18, 0x3e000000, v4
	v_lshlrev_b32_e32 v5, 16, v6
	v_lshlrev_b32_e32 v4, 16, v10
	v_mov_b32_e32 v8, v20
	v_mov_b32_e32 v9, v12
	v_pk_mul_f32 v[8:9], v[8:9], v[4:5]
	v_mul_f32_e32 v1, 0x3e000000, v1
	v_sub_f32_e32 v8, v9, v8
	v_mul_f32_e32 v19, 0x3e000000, v8
	v_mov_b32_e32 v8, v12
	v_mov_b32_e32 v9, v20
	v_pk_mul_f32 v[4:5], v[8:9], v[4:5]
	v_mov_b32_e32 v12, v21
	v_add_f32_e32 v4, v4, v5
	v_mul_f32_e32 v59, 0x3e000000, v4
	v_and_b32_e32 v5, 0xffff0000, v6
	v_and_b32_e32 v4, 0xffff0000, v10
	v_mov_b32_e32 v20, v13
	v_pk_mul_f32 v[8:9], v[12:13], v[4:5]
	v_pk_mul_f32 v[4:5], v[20:21], v[4:5]
	v_sub_f32_e32 v6, v9, v8
	v_add_f32_e32 v4, v4, v5
	v_mul_f32_e32 v12, 0x3e000000, v4
	v_lshlrev_b32_e32 v5, 16, v7
	v_lshlrev_b32_e32 v4, 16, v11
	v_mov_b32_e32 v8, v22
	v_mov_b32_e32 v9, v14
	v_pk_mul_f32 v[8:9], v[8:9], v[4:5]
	v_mul_f32_e32 v10, 0x3e000000, v6
	v_sub_f32_e32 v6, v9, v8
	v_mov_b32_e32 v8, v14
	v_mov_b32_e32 v9, v22
	v_pk_mul_f32 v[4:5], v[8:9], v[4:5]
	v_mov_b32_e32 v14, v23
	v_add_f32_e32 v4, v4, v5
	v_mul_f32_e32 v8, 0x3e000000, v4
	v_and_b32_e32 v5, 0xffff0000, v7
	v_and_b32_e32 v4, 0xffff0000, v11
	v_mov_b32_e32 v22, v15
	v_mul_f32_e32 v13, 0x3e000000, v6
	v_pk_mul_f32 v[6:7], v[14:15], v[4:5]
	v_pk_mul_f32 v[4:5], v[22:23], v[4:5]
	v_sub_f32_e32 v6, v7, v6
	v_add_f32_e32 v4, v4, v5
	v_mul_f32_e32 v6, 0x3e000000, v6
	v_mul_f32_e32 v4, 0x3e000000, v4
	v_cvt_pk_bf16_f32 v1, v1, v53
	v_cvt_pk_bf16_f32 v5, v57, v17
	v_cvt_pk_bf16_f32 v6, v13, v6
	v_cvt_pk_bf16_f32 v9, v51, v55
	v_cvt_pk_bf16_f32 v4, v8, v4
	v_cvt_pk_bf16_f32 v7, v19, v10
	v_cvt_pk_bf16_f32 v10, v16, v18
	v_cvt_pk_bf16_f32 v11, v59, v12
	v_add_u32_e32 v12, -16, v0
	v_cndmask_b32_e32 v1, v9, v1, vcc
	v_cndmask_b32_e32 v4, v4, v6, vcc
	v_cndmask_b32_e32 v6, v11, v7, vcc
	v_cndmask_b32_e32 v5, v10, v5, vcc
	ds_write_b16 v29, v1 offset:64
	ds_write_b16_d16_hi v29, v1 offset:208
	ds_write_b16 v29, v5 offset:352
	ds_write_b16_d16_hi v29, v5 offset:496
	ds_write_b16 v29, v6 offset:640
	ds_write_b16_d16_hi v29, v6 offset:784
	ds_write_b16 v29, v4 offset:928
	ds_write_b16_d16_hi v29, v4 offset:1072
	v_or_b32_e32 v1, s20, v36
	v_mad_u64_u32 v[4:5], s[0:1], v1, s5, v[2:3]
	v_mad_i32_i24 v5, s17, v207, v5
	v_ashrrev_i32_e32 v13, 31, v12
	v_lshl_add_u64 v[4:5], v[4:5], 0, s[38:39]
	v_lshlrev_b64 v[12:13], 7, v[12:13]
	v_lshl_add_u64 v[8:9], v[4:5], 0, v[60:61]
	v_lshl_add_u64 v[16:17], v[44:45], 0, v[12:13]
	v_lshl_add_u64 v[66:67], v[46:47], 0, v[12:13]
	s_waitcnt vmcnt(6)
; #define LAS __attribute__((address_space(3)))
; __device__ __forceinline__ unsigned pk2(float lo, float hi) { unsigned r; asm("v_cvt_pk_bf16_f32 %0, %1, %2" : "=v"(r) : "v"(lo), "v"(hi)); return r; }
; __device__ __forceinline__ void rot8(u32x4 x1, u32x4 x2, const float* cs, const float* sn, float sc, u32x4& o1, u32x4& o2) {
;     const f32x4 c0 = *(const f32x4*)cs, c1 = *(const f32x4*)(cs + 4), s0 = *(const f32x4*)sn, s1 = *(const f32x4*)(sn + 4);
;     float a[8], b[8], c[8], s[8];
;     a[0] = bflo(x1.x); a[1] = bfhi(x1.x); a[2] = bflo(x1.y); a[3] = bfhi(x1.y); a[4] = bflo(x1.z); a[5] = bfhi(x1.z); a[6] = bflo(x1.w); a[7] = bfhi(x1.w);
;     b[0] = bflo(x2.x); b[1] = bfhi(x2.x); b[2] = bflo(x2.y); b[3] = bfhi(x2.y); b[4] = bflo(x2.z); b[5] = bfhi(x2.z); b[6] = bflo(x2.w); b[7] = bfhi(x2.w);
; #pragma unroll
;     for (int i = 0; i < 4; ++i) { c[i] = c0[i]; c[4 + i] = c1[i]; s[i] = s0[i]; s[4 + i] = s1[i]; }
;     float p[8], q[8];
; #pragma unroll
;     for (int i = 0; i < 8; ++i) { p[i] = (a[i] * c[i] - b[i] * s[i]) * sc; q[i] = (a[i] * s[i] + b[i] * c[i]) * sc; }
;     o1.x = pk2(p[0], p[1]); o1.y = pk2(p[2], p[3]); o1.z = pk2(p[4], p[5]); o1.w = pk2(p[6], p[7]);
;     o2.x = pk2(q[0], q[1]); o2.y = pk2(q[2], q[3]); o2.z = pk2(q[4], q[5]); o2.w = pk2(q[6], q[7]);
; __device__ __forceinline__ void retkv_item(const bf16_t* hbuf, const float* rot, float* kvbuf, LAS bf16_t* wl, int item, int lane) {
;     ...
;     { const int cr = lane >> 3, dc = lane & 7, fc = dc & 3;
; #pragma unroll
;       for (int i = 0; i < 8; ++i) { const int row = cr + 8 * i; const bf16_t* kp = hbuf + (t0 + row) * INWP + C_RK + h * 64;
;           const u32x4 x1 = *(const u32x4*)(kp + 8 * fc), x2 = *(const u32x4*)(kp + 32 + 8 * fc);
;           const int pos = n * 64 + row; u32x4 o1, o2;
;           rot8(x1, x2, rot + (size_t)pos * 32 + 8 * fc, rot + 16384 * 32 + (size_t)pos * 32 + 8 * fc, 0.125f, o1, o2);
;           const u32x4 w = dc < 4 ? o1 : o2;
;           LAS bf16_t* t = kT + (8 * dc) * TLD + row;
;           t[0 * TLD] = (bf16_t)(w.x & 0xffff); t[1 * TLD] = (bf16_t)(w.x >> 16); t[2 * TLD] = (bf16_t)(w.y & 0xffff); t[3 * TLD] = (bf16_t)(w.y >> 16);
;           t[4 * TLD] = (bf16_t)(w.z & 0xffff); t[5 * TLD] = (bf16_t)(w.z >> 16); t[6 * TLD] = (bf16_t)(w.w & 0xffff); t[7 * TLD] = (bf16_t)(w.w >> 16); } }
	v_mov_b64_e32 v[4:5], v[92:93]
	v_mov_b64_e32 v[6:7], v[94:95]
	v_mov_b64_e32 v[8:9], v[96:97]
	v_mov_b64_e32 v[10:11], v[98:99]
	v_mov_b64_e32 v[12:13], v[100:101]
	v_mov_b64_e32 v[14:15], v[102:103]
	v_mov_b64_e32 v[16:17], v[104:105]
	v_mov_b64_e32 v[18:19], v[106:107]
	v_mov_b64_e32 v[20:21], v[108:109]
	v_mov_b64_e32 v[22:23], v[110:111]
	v_mov_b64_e32 v[66:67], v[112:113]
	v_mov_b64_e32 v[68:69], v[114:115]
	v_lshlrev_b32_e32 v71, 16, v4
	v_lshlrev_b32_e32 v70, 16, v8
	v_mov_b32_e32 v72, v66
	v_mov_b32_e32 v73, v16
	v_pk_mul_f32 v[72:73], v[72:73], v[70:71]
	s_nop 0
	v_sub_f32_e32 v1, v73, v72
	v_mov_b32_e32 v72, v16
	v_mov_b32_e32 v73, v66
	v_pk_mul_f32 v[70:71], v[72:73], v[70:71]
	v_mov_b32_e32 v66, v17
	v_add_f32_e32 v16, v70, v71
	v_mul_f32_e32 v51, 0x3e000000, v16
	v_and_b32_e32 v71, 0xffff0000, v4
	v_and_b32_e32 v70, 0xffff0000, v8
	v_mov_b32_e32 v16, v67
	v_pk_mul_f32 v[72:73], v[16:17], v[70:71]
	v_pk_mul_f32 v[16:17], v[66:67], v[70:71]
	v_sub_f32_e32 v4, v73, v72
	v_mul_f32_e32 v53, 0x3e000000, v4
	v_add_f32_e32 v4, v16, v17
	v_lshlrev_b32_e32 v17, 16, v5
	v_lshlrev_b32_e32 v16, 16, v9
	v_mov_b32_e32 v66, v68
	v_mov_b32_e32 v67, v18
	v_pk_mul_f32 v[66:67], v[66:67], v[16:17]
	v_mul_f32_e32 v55, 0x3e000000, v4
	v_sub_f32_e32 v4, v67, v66
	v_mov_b32_e32 v66, v18
	v_mov_b32_e32 v67, v68
	v_pk_mul_f32 v[16:17], v[66:67], v[16:17]
	v_mul_f32_e32 v57, 0x3e000000, v4
	v_add_f32_e32 v4, v16, v17
	v_mul_f32_e32 v16, 0x3e000000, v4
	v_and_b32_e32 v5, 0xffff0000, v5
	v_and_b32_e32 v4, 0xffff0000, v9
	v_mov_b32_e32 v18, v69
	v_mov_b32_e32 v68, v19
	v_pk_mul_f32 v[8:9], v[18:19], v[4:5]
	v_pk_mul_f32 v[4:5], v[68:69], v[4:5]
	v_sub_f32_e32 v8, v9, v8
	v_add_f32_e32 v4, v4, v5
	v_mul_f32_e32 v17, 0x3e000000, v8
	v_mul_f32_e32 v18, 0x3e000000, v4
	v_lshlrev_b32_e32 v5, 16, v6
	v_lshlrev_b32_e32 v4, 16, v10
	v_mov_b32_e32 v8, v20
	v_mov_b32_e32 v9, v12
	v_pk_mul_f32 v[8:9], v[8:9], v[4:5]
	v_mul_f32_e32 v1, 0x3e000000, v1
	v_sub_f32_e32 v8, v9, v8
	v_mul_f32_e32 v19, 0x3e000000, v8
	v_mov_b32_e32 v8, v12
	v_mov_b32_e32 v9, v20
	v_pk_mul_f32 v[4:5], v[8:9], v[4:5]
	v_mov_b32_e32 v12, v21
	v_add_f32_e32 v4, v4, v5
	v_mul_f32_e32 v59, 0x3e000000, v4
	v_and_b32_e32 v5, 0xffff0000, v6
	v_and_b32_e32 v4, 0xffff0000, v10
	v_mov_b32_e32 v20, v13
	v_pk_mul_f32 v[8:9], v[12:13], v[4:5]
	v_pk_mul_f32 v[4:5], v[20:21], v[4:5]
	v_sub_f32_e32 v6, v9, v8
	v_add_f32_e32 v4, v4, v5
	v_mul_f32_e32 v12, 0x3e000000, v4
	v_lshlrev_b32_e32 v5, 16, v7
	v_lshlrev_b32_e32 v4, 16, v11
	v_mov_b32_e32 v8, v22
	v_mov_b32_e32 v9, v14
	v_pk_mul_f32 v[8:9], v[8:9], v[4:5]
	v_mul_f32_e32 v10, 0x3e000000, v6
	v_sub_f32_e32 v6, v9, v8
	v_mov_b32_e32 v8, v14
	v_mov_b32_e32 v9, v22
	v_pk_mul_f32 v[4:5], v[8:9], v[4:5]
	v_mov_b32_e32 v14, v23
	v_add_f32_e32 v4, v4, v5
	v_mul_f32_e32 v8, 0x3e000000, v4
	v_and_b32_e32 v5, 0xffff0000, v7
	v_and_b32_e32 v4, 0xffff0000, v11
	v_mov_b32_e32 v22, v15
	v_mul_f32_e32 v13, 0x3e000000, v6
	v_pk_mul_f32 v[6:7], v[14:15], v[4:5]
	v_pk_mul_f32 v[4:5], v[22:23], v[4:5]
	v_sub_f32_e32 v6, v7, v6
	v_add_f32_e32 v4, v4, v5
	v_mul_f32_e32 v6, 0x3e000000, v6
	v_mul_f32_e32 v4, 0x3e000000, v4
	v_cvt_pk_bf16_f32 v1, v1, v53
	v_cvt_pk_bf16_f32 v5, v57, v17
	v_cvt_pk_bf16_f32 v6, v13, v6
	v_cvt_pk_bf16_f32 v9, v51, v55
	v_cvt_pk_bf16_f32 v4, v8, v4
	v_cvt_pk_bf16_f32 v7, v19, v10
	v_cvt_pk_bf16_f32 v10, v16, v18
	v_cvt_pk_bf16_f32 v11, v59, v12
	v_add_u32_e32 v12, -8, v0
	v_cndmask_b32_e32 v1, v9, v1, vcc
	v_cndmask_b32_e32 v4, v4, v6, vcc
	v_cndmask_b32_e32 v6, v11, v7, vcc
	v_cndmask_b32_e32 v5, v10, v5, vcc
	ds_write_b16 v29, v1 offset:80
	ds_write_b16_d16_hi v29, v1 offset:224
	ds_write_b16 v29, v5 offset:368
	ds_write_b16_d16_hi v29, v5 offset:512
	ds_write_b16 v29, v6 offset:656
	ds_write_b16_d16_hi v29, v6 offset:800
	ds_write_b16 v29, v4 offset:944
	ds_write_b16_d16_hi v29, v4 offset:1088
	v_or_b32_e32 v1, s20, v40
	v_mad_u64_u32 v[4:5], s[0:1], v1, s5, v[2:3]
	v_mad_i32_i24 v5, s17, v207, v5
	v_ashrrev_i32_e32 v13, 31, v12
	v_lshl_add_u64 v[4:5], v[4:5], 0, s[38:39]
	v_lshlrev_b64 v[12:13], 7, v[12:13]
	v_lshl_add_u64 v[8:9], v[4:5], 0, v[60:61]
	v_lshl_add_u64 v[16:17], v[44:45], 0, v[12:13]
	v_lshl_add_u64 v[66:67], v[46:47], 0, v[12:13]
	s_waitcnt vmcnt(0)
; #define LAS __attribute__((address_space(3)))
; __device__ __forceinline__ float bflo(unsigned u) { return __uint_as_float(u << 16); }
; __device__ __forceinline__ void rot8(u32x4 x1, u32x4 x2, const float* cs, const float* sn, float sc, u32x4& o1, u32x4& o2) {
;     const f32x4 c0 = *(const f32x4*)cs, c1 = *(const f32x4*)(cs + 4), s0 = *(const f32x4*)sn, s1 = *(const f32x4*)(sn + 4);
;     float a[8], b[8], c[8], s[8];
;     a[0] = bflo(x1.x); a[1] = bfhi(x1.x); a[2] = bflo(x1.y); a[3] = bfhi(x1.y); a[4] = bflo(x1.z); a[5] = bfhi(x1.z); a[6] = bflo(x1.w); a[7] = bfhi(x1.w);
;     b[0] = bflo(x2.x); b[1] = bfhi(x2.x); b[2] = bflo(x2.y); b[3] = bfhi(x2.y); b[4] = bflo(x2.z); b[5] = bfhi(x2.z); b[6] = bflo(x2.w); b[7] = bfhi(x2.w);
; #pragma unroll
;     for (int i = 0; i < 4; ++i) { c[i] = c0[i]; c[4 + i] = c1[i]; s[i] = s0[i]; s[4 + i] = s1[i]; }
;     float p[8], q[8];
; #pragma unroll
;     for (int i = 0; i < 8; ++i) { p[i] = (a[i] * c[i] - b[i] * s[i]) * sc; q[i] = (a[i] * s[i] + b[i] * c[i]) * sc; }
;     o1.x = pk2(p[0], p[1]); o1.y = pk2(p[2], p[3]); o1.z = pk2(p[4], p[5]); o1.w = pk2(p[6], p[7]);
;     o2.x = pk2(q[0], q[1]); o2.y = pk2(q[2], q[3]); o2.z = pk2(q[4], q[5]); o2.w = pk2(q[6], q[7]);
; __device__ __forceinline__ void retkv_item(const bf16_t* hbuf, const float* rot, float* kvbuf, LAS bf16_t* wl, int item, int lane) {
;     ...
;     { const int cr = lane >> 3, dc = lane & 7, fc = dc & 3;
; #pragma unroll
;       for (int i = 0; i < 8; ++i) { const int row = cr + 8 * i; const bf16_t* kp = hbuf + (t0 + row) * INWP + C_RK + h * 64;
;           const u32x4 x1 = *(const u32x4*)(kp + 8 * fc), x2 = *(const u32x4*)(kp + 32 + 8 * fc);
;           const int pos = n * 64 + row; u32x4 o1, o2;
;           rot8(x1, x2, rot + (size_t)pos * 32 + 8 * fc, rot + 16384 * 32 + (size_t)pos * 32 + 8 * fc, 0.125f, o1, o2);
;           const u32x4 w = dc < 4 ? o1 : o2;
;           LAS bf16_t* t = kT + (8 * dc) * TLD + row;
;           t[0 * TLD] = (bf16_t)(w.x & 0xffff); t[1 * TLD] = (bf16_t)(w.x >> 16); t[2 * TLD] = (bf16_t)(w.y & 0xffff); t[3 * TLD] = (bf16_t)(w.y >> 16);
;           t[4 * TLD] = (bf16_t)(w.z & 0xffff); t[5 * TLD] = (bf16_t)(w.z >> 16); t[6 * TLD] = (bf16_t)(w.w & 0xffff); t[7 * TLD] = (bf16_t)(w.w >> 16); } }
;     lds_fence();
;     const int r = lane & 15, q = lane >> 4;
;     float* outp = kvbuf + (size_t)item * 4096;
	v_mov_b64_e32 v[4:5], v[116:117]
	v_mov_b64_e32 v[6:7], v[118:119]
	v_mov_b64_e32 v[8:9], v[120:121]
	v_mov_b64_e32 v[10:11], v[122:123]
	v_mov_b64_e32 v[12:13], v[124:125]
	v_mov_b64_e32 v[14:15], v[126:127]
	v_mov_b64_e32 v[16:17], v[128:129]
	v_mov_b64_e32 v[18:19], v[130:131]
	v_mov_b64_e32 v[20:21], v[132:133]
	v_mov_b64_e32 v[22:23], v[134:135]
	v_mov_b64_e32 v[66:67], v[136:137]
	v_mov_b64_e32 v[68:69], v[138:139]
	v_lshlrev_b32_e32 v71, 16, v4
	v_lshlrev_b32_e32 v70, 16, v8
	v_mov_b32_e32 v72, v66
	v_mov_b32_e32 v73, v16
	v_pk_mul_f32 v[72:73], v[72:73], v[70:71]
	s_nop 0
	v_sub_f32_e32 v1, v73, v72
	v_mov_b32_e32 v72, v16
	v_mov_b32_e32 v73, v66
	v_pk_mul_f32 v[70:71], v[72:73], v[70:71]
	v_mov_b32_e32 v66, v17
	v_add_f32_e32 v16, v70, v71
	v_mul_f32_e32 v51, 0x3e000000, v16
	v_and_b32_e32 v71, 0xffff0000, v4
	v_and_b32_e32 v70, 0xffff0000, v8
	v_mov_b32_e32 v16, v67
	v_pk_mul_f32 v[72:73], v[16:17], v[70:71]
	v_pk_mul_f32 v[16:17], v[66:67], v[70:71]
	v_sub_f32_e32 v4, v73, v72
	v_mul_f32_e32 v53, 0x3e000000, v4
	v_add_f32_e32 v4, v16, v17
	v_lshlrev_b32_e32 v17, 16, v5
	v_lshlrev_b32_e32 v16, 16, v9
	v_mov_b32_e32 v66, v68
	v_mov_b32_e32 v67, v18
	v_pk_mul_f32 v[66:67], v[66:67], v[16:17]
	v_mul_f32_e32 v55, 0x3e000000, v4
	v_sub_f32_e32 v4, v67, v66
	v_mov_b32_e32 v66, v18
	v_mov_b32_e32 v67, v68
	v_pk_mul_f32 v[16:17], v[66:67], v[16:17]
	v_mul_f32_e32 v57, 0x3e000000, v4
	v_add_f32_e32 v4, v16, v17
	v_mul_f32_e32 v16, 0x3e000000, v4
	v_and_b32_e32 v5, 0xffff0000, v5
	v_and_b32_e32 v4, 0xffff0000, v9
	v_mov_b32_e32 v18, v69
	v_mov_b32_e32 v68, v19
	v_pk_mul_f32 v[8:9], v[18:19], v[4:5]
	v_pk_mul_f32 v[4:5], v[68:69], v[4:5]
	v_sub_f32_e32 v8, v9, v8
	v_add_f32_e32 v4, v4, v5
	v_mul_f32_e32 v17, 0x3e000000, v8
	v_mul_f32_e32 v18, 0x3e000000, v4
	v_lshlrev_b32_e32 v5, 16, v6
	v_lshlrev_b32_e32 v4, 16, v10
	v_mov_b32_e32 v8, v20
	v_mov_b32_e32 v9, v12
	v_pk_mul_f32 v[8:9], v[8:9], v[4:5]
	v_mul_f32_e32 v1, 0x3e000000, v1
	v_sub_f32_e32 v8, v9, v8
	v_mul_f32_e32 v19, 0x3e000000, v8
	v_mov_b32_e32 v8, v12
	v_mov_b32_e32 v9, v20
	v_pk_mul_f32 v[4:5], v[8:9], v[4:5]
	v_mov_b32_e32 v12, v21
	v_add_f32_e32 v4, v4, v5
	v_mul_f32_e32 v59, 0x3e000000, v4
	v_and_b32_e32 v5, 0xffff0000, v6
	v_and_b32_e32 v4, 0xffff0000, v10
	v_mov_b32_e32 v20, v13
	v_pk_mul_f32 v[8:9], v[12:13], v[4:5]
	v_pk_mul_f32 v[4:5], v[20:21], v[4:5]
	v_sub_f32_e32 v6, v9, v8
	v_add_f32_e32 v4, v4, v5
	v_mul_f32_e32 v12, 0x3e000000, v4
	v_lshlrev_b32_e32 v5, 16, v7
	v_lshlrev_b32_e32 v4, 16, v11
	v_mov_b32_e32 v8, v22
	v_mov_b32_e32 v9, v14
	v_pk_mul_f32 v[8:9], v[8:9], v[4:5]
	v_mul_f32_e32 v10, 0x3e000000, v6
	v_sub_f32_e32 v6, v9, v8
	v_mov_b32_e32 v8, v14
	v_mov_b32_e32 v9, v22
	v_pk_mul_f32 v[4:5], v[8:9], v[4:5]
	v_mov_b32_e32 v14, v23
	v_add_f32_e32 v4, v4, v5
	v_mul_f32_e32 v8, 0x3e000000, v4
	v_and_b32_e32 v5, 0xffff0000, v7
	v_and_b32_e32 v4, 0xffff0000, v11
	v_mov_b32_e32 v22, v15
	v_mul_f32_e32 v13, 0x3e000000, v6
	v_pk_mul_f32 v[6:7], v[14:15], v[4:5]
	v_pk_mul_f32 v[4:5], v[22:23], v[4:5]
	v_sub_f32_e32 v6, v7, v6
	v_add_f32_e32 v4, v4, v5
	v_mul_f32_e32 v6, 0x3e000000, v6
	v_mul_f32_e32 v4, 0x3e000000, v4
	v_cvt_pk_bf16_f32 v1, v1, v53
	v_cvt_pk_bf16_f32 v5, v57, v17
	v_cvt_pk_bf16_f32 v6, v13, v6
	v_cvt_pk_bf16_f32 v9, v51, v55
	v_cvt_pk_bf16_f32 v4, v8, v4
	v_cvt_pk_bf16_f32 v7, v19, v10
	v_cvt_pk_bf16_f32 v10, v16, v18
	v_cvt_pk_bf16_f32 v11, v59, v12
	s_nop 0
	v_cndmask_b32_e32 v1, v9, v1, vcc
	v_cndmask_b32_e32 v4, v4, v6, vcc
	v_cndmask_b32_e32 v6, v11, v7, vcc
	v_cndmask_b32_e32 v5, v10, v5, vcc
	ds_write_b16 v29, v1 offset:96
	ds_write_b16_d16_hi v29, v1 offset:240
	ds_write_b16 v29, v5 offset:384
	ds_write_b16_d16_hi v29, v5 offset:528
	ds_write_b16 v29, v6 offset:672
	ds_write_b16_d16_hi v29, v6 offset:816
	ds_write_b16 v29, v4 offset:960
	ds_write_b16_d16_hi v29, v4 offset:1104
	v_or_b32_e32 v1, s20, v42
	v_mad_u64_u32 v[2:3], s[0:1], v1, s5, v[2:3]
	v_mad_i32_i24 v3, s17, v207, v3
	v_lshl_add_u64 v[2:3], v[2:3], 0, s[38:39]
	v_ashrrev_i32_e32 v1, 31, v0
	v_lshl_add_u64 v[2:3], v[2:3], 0, v[60:61]
	v_lshlrev_b64 v[0:1], 7, v[0:1]
	global_load_dwordx4 v[8:11], v[2:3], off offset:3584
	global_load_dwordx4 v[12:15], v[2:3], off offset:3648
	v_lshl_add_u64 v[2:3], v[44:45], 0, v[0:1]
	v_lshl_add_u64 v[20:21], v[46:47], 0, v[0:1]
	global_load_dwordx4 v[4:7], v[2:3], off offset:16
	global_load_dwordx4 v[16:19], v[2:3], off
	s_nop 0
	global_load_dwordx4 v[0:3], v[20:21], off offset:16
	s_nop 0
	global_load_dwordx4 v[20:23], v[20:21], off
	s_lshl_b64 s[0:1], s[36:37], 14
	v_lshl_add_u64 v[86:87], v[48:49], 0, s[0:1]
	v_add_co_u32_e64 v88, s[0:1], s45, v86
	s_add_i32 s36, s36, s14
	s_nop 0
	v_addc_co_u32_e64 v89, s[0:1], 0, v87, s[0:1]
	v_add_co_u32_e64 v90, s[0:1], s27, v86
	s_cmpk_gt_i32 s36, 0xbff
	s_nop 0
	v_addc_co_u32_e64 v91, s[0:1], 0, v87, s[0:1]
	s_waitcnt vmcnt(5)
	v_lshlrev_b32_e32 v67, 16, v8
	s_waitcnt vmcnt(4)
	v_lshlrev_b32_e32 v66, 16, v12
	s_waitcnt vmcnt(2)
	v_mov_b32_e32 v69, v16
	s_waitcnt vmcnt(0)
; #define LAS __attribute__((address_space(3)))
; __device__ __forceinline__ void lds_fence() { asm volatile("s_waitcnt lgkmcnt(0)" ::: "memory"); }
; __device__ __forceinline__ void retkv_item(const bf16_t* hbuf, const float* rot, float* kvbuf, LAS bf16_t* wl, int item, int lane) {
;     ...
;       for (int i = 0; i < 8; ++i) { const int row = cr + 8 * i; const bf16_t* kp = hbuf + (t0 + row) * INWP + C_RK + h * 64;
;           const u32x4 x1 = *(const u32x4*)(kp + 8 * fc), x2 = *(const u32x4*)(kp + 32 + 8 * fc);
;           const int pos = n * 64 + row; u32x4 o1, o2;
;           rot8(x1, x2, rot + (size_t)pos * 32 + 8 * fc, rot + 16384 * 32 + (size_t)pos * 32 + 8 * fc, 0.125f, o1, o2);
;           const u32x4 w = dc < 4 ? o1 : o2;
;           LAS bf16_t* t = kT + (8 * dc) * TLD + row;
;           t[0 * TLD] = (bf16_t)(w.x & 0xffff); t[1 * TLD] = (bf16_t)(w.x >> 16); t[2 * TLD] = (bf16_t)(w.y & 0xffff); t[3 * TLD] = (bf16_t)(w.y >> 16);
;           t[4 * TLD] = (bf16_t)(w.z & 0xffff); t[5 * TLD] = (bf16_t)(w.z >> 16); t[6 * TLD] = (bf16_t)(w.w & 0xffff); t[7 * TLD] = (bf16_t)(w.w >> 16); } }
;     lds_fence();
;     const int r = lane & 15, q = lane >> 4;
;     float* outp = kvbuf + (size_t)item * 4096;
; #pragma unroll
;     for (int et = 0; et < 4; ++et) {
;         bf16x8 vf[2];
; #pragma unroll
;         for (int ks = 0; ks < 2; ++ks) vf[ks] = *(const LAS bf16x8*)(vT + (16 * et + r) * TLD + 32 * ks + 8 * q);
; #pragma unroll
;         for (int dt = 0; dt < 4; ++dt) { f32x4 acc = {0.f, 0.f, 0.f, 0.f};
; #pragma unroll
;             for (int ks = 0; ks < 2; ++ks) { const bf16x8 kf = *(const LAS bf16x8*)(kT + (16 * dt + r) * TLD + 32 * ks + 8 * q);
;                 acc = __builtin_amdgcn_mfma_f32_16x16x32_bf16(kf, vf[ks], acc, 0, 0, 0); }
;             *(f32x4*)(outp + (16 * et + r) * 64 + 16 * dt + 4 * q) = acc; } }
	v_mov_b32_e32 v68, v20
	v_pk_mul_f32 v[68:69], v[68:69], v[66:67]
	s_nop 0
	v_sub_f32_e32 v51, v69, v68
	v_mov_b32_e32 v68, v16
	v_mov_b32_e32 v69, v20
	v_pk_mul_f32 v[66:67], v[68:69], v[66:67]
	v_mov_b32_e32 v20, v17
	v_add_f32_e32 v16, v66, v67
	v_mul_f32_e32 v53, 0x3e000000, v16
	v_and_b32_e32 v67, 0xffff0000, v8
	v_and_b32_e32 v66, 0xffff0000, v12
	v_mov_b32_e32 v16, v21
	v_pk_mul_f32 v[68:69], v[16:17], v[66:67]
	v_pk_mul_f32 v[16:17], v[20:21], v[66:67]
	v_lshlrev_b32_e32 v21, 16, v9
	v_add_f32_e32 v12, v16, v17
	v_lshlrev_b32_e32 v20, 16, v13
	v_mov_b32_e32 v16, v22
	v_mov_b32_e32 v17, v18
	v_mov_b32_e32 v66, v18
	v_mov_b32_e32 v67, v22
	v_pk_mul_f32 v[16:17], v[16:17], v[20:21]
	v_pk_mul_f32 v[20:21], v[66:67], v[20:21]
	v_sub_f32_e32 v16, v17, v16
	v_add_f32_e32 v17, v20, v21
	v_and_b32_e32 v21, 0xffff0000, v9
	v_and_b32_e32 v20, 0xffff0000, v13
	v_mov_b32_e32 v18, v23
	v_mov_b32_e32 v22, v19
	v_pk_mul_f32 v[66:67], v[18:19], v[20:21]
	v_pk_mul_f32 v[18:19], v[22:23], v[20:21]
	v_lshlrev_b32_e32 v21, 16, v10
	v_add_f32_e32 v13, v18, v19
	v_lshlrev_b32_e32 v20, 16, v14
	v_mov_b32_e32 v18, v0
	v_mov_b32_e32 v19, v4
	v_mov_b32_e32 v22, v4
	v_mov_b32_e32 v23, v0
	v_pk_mul_f32 v[18:19], v[18:19], v[20:21]
	v_pk_mul_f32 v[20:21], v[22:23], v[20:21]
	v_mov_b32_e32 v4, v1
	v_add_f32_e32 v0, v20, v21
	v_and_b32_e32 v21, 0xffff0000, v10
	v_and_b32_e32 v20, 0xffff0000, v14
	v_pk_mul_f32 v[22:23], v[4:5], v[20:21]
	v_sub_f32_e32 v18, v19, v18
	v_mul_f32_e32 v19, 0x3e000000, v0
	v_sub_f32_e32 v0, v23, v22
	v_mul_f32_e32 v4, 0x3e000000, v0
	v_mov_b32_e32 v0, v5
	v_pk_mul_f32 v[0:1], v[0:1], v[20:21]
	v_mov_b32_e32 v20, v2
	v_add_f32_e32 v0, v0, v1
	v_mul_f32_e32 v5, 0x3e000000, v0
	v_lshlrev_b32_e32 v1, 16, v11
	v_lshlrev_b32_e32 v0, 16, v15
	v_mov_b32_e32 v21, v6
	v_pk_mul_f32 v[20:21], v[20:21], v[0:1]
	v_sub_f32_e32 v8, v69, v68
	v_sub_f32_e32 v10, v21, v20
	v_mov_b32_e32 v20, v6
	v_mov_b32_e32 v21, v2
	v_pk_mul_f32 v[0:1], v[20:21], v[0:1]
	v_mov_b32_e32 v6, v3
	v_add_f32_e32 v0, v0, v1
	v_mul_f32_e32 v14, 0x3e000000, v0
	v_and_b32_e32 v1, 0xffff0000, v11
	v_and_b32_e32 v0, 0xffff0000, v15
	v_pk_mul_f32 v[20:21], v[6:7], v[0:1]
	v_mul_f32_e32 v51, 0x3e000000, v51
	v_sub_f32_e32 v2, v21, v20
	v_mul_f32_e32 v6, 0x3e000000, v2
	v_mov_b32_e32 v2, v7
	v_pk_mul_f32 v[0:1], v[2:3], v[0:1]
	v_mul_f32_e32 v8, 0x3e000000, v8
	v_add_f32_e32 v0, v0, v1
	v_sub_f32_e32 v9, v67, v66
	v_mul_f32_e32 v0, 0x3e000000, v0
	v_cvt_pk_bf16_f32 v1, v51, v8
	v_mul_f32_e32 v12, 0x3e000000, v12
	v_mul_f32_e32 v16, 0x3e000000, v16
	v_mul_f32_e32 v9, 0x3e000000, v9
	v_mul_f32_e32 v18, 0x3e000000, v18
	v_mul_f32_e32 v10, 0x3e000000, v10
	v_cvt_pk_bf16_f32 v2, v16, v9
	v_cvt_pk_bf16_f32 v3, v18, v4
	v_cvt_pk_bf16_f32 v4, v10, v6
	v_cvt_pk_bf16_f32 v6, v53, v12
	v_cvt_pk_bf16_f32 v0, v14, v0
	v_mul_f32_e32 v17, 0x3e000000, v17
	v_cndmask_b32_e32 v1, v6, v1, vcc
	v_mul_f32_e32 v13, 0x3e000000, v13
	v_cvt_pk_bf16_f32 v7, v17, v13
	v_cvt_pk_bf16_f32 v5, v19, v5
	v_cndmask_b32_e32 v0, v0, v4, vcc
	v_cndmask_b32_e32 v3, v5, v3, vcc
	v_cndmask_b32_e32 v2, v7, v2, vcc
	ds_write_b16 v29, v1 offset:112
	ds_write_b16_d16_hi v29, v1 offset:256
	ds_write_b16 v29, v2 offset:400
	ds_write_b16_d16_hi v29, v2 offset:544
	ds_write_b16 v29, v3 offset:688
	ds_write_b16_d16_hi v29, v3 offset:832
	ds_write_b16 v29, v0 offset:976
	ds_write_b16_d16_hi v29, v0 offset:1120
	s_waitcnt lgkmcnt(0)
	ds_read_b128 v[0:3], v64 offset:9216
	ds_read_b128 v[4:7], v64 offset:9280
	ds_read_b128 v[8:11], v64
	ds_read_b128 v[16:19], v64 offset:64
	s_waitcnt lgkmcnt(1)
	v_mfma_f32_16x16x32_bf16 v[12:15], v[8:11], v[0:3], 0
	ds_read_b128 v[66:69], v64 offset:2368
	ds_read_b128 v[74:77], v64 offset:4672
	s_waitcnt lgkmcnt(2)
	v_mfma_f32_16x16x32_bf16 v[12:15], v[16:19], v[4:7], v[12:15]
	s_nop 7
	global_store_dwordx4 v[86:87], v[12:15], off nt
	ds_read_b128 v[12:15], v64 offset:2304
	s_waitcnt lgkmcnt(0)
; #define LAS __attribute__((address_space(3)))
; __device__ __forceinline__ void lds_fence() { asm volatile("s_waitcnt lgkmcnt(0)" ::: "memory"); }
; __device__ __forceinline__ void retkv_item(const bf16_t* hbuf, const float* rot, float* kvbuf, LAS bf16_t* wl, int item, int lane) {
;     ...
;         for (int ks = 0; ks < 2; ++ks) vf[ks] = *(const LAS bf16x8*)(vT + (16 * et + r) * TLD + 32 * ks + 8 * q);
; #pragma unroll
;         for (int dt = 0; dt < 4; ++dt) { f32x4 acc = {0.f, 0.f, 0.f, 0.f};
; #pragma unroll
;             for (int ks = 0; ks < 2; ++ks) { const bf16x8 kf = *(const LAS bf16x8*)(kT + (16 * dt + r) * TLD + 32 * ks + 8 * q);
;                 acc = __builtin_amdgcn_mfma_f32_16x16x32_bf16(kf, vf[ks], acc, 0, 0, 0); }
;             *(f32x4*)(outp + (16 * et + r) * 64 + 16 * dt + 4 * q) = acc; } }
;     lds_fence();
; __device__ __forceinline__ void run_phase(const Args& a, const int ph, LAS unsigned char* lds, const int tid, const int rpt) {
;     ...
;                 for (int it = gw; it < 12 * NCHUNK; it += NGW) retkv_item(hbuf, rot, kvbuf, wl, it, lane);
;                 for (int it = gw; it < 12 * NCHUNK; it += NGW) knorm_item(hbuf, kmax2, it, lane);
	v_mfma_f32_16x16x32_bf16 v[20:23], v[12:15], v[0:3], 0
	v_mfma_f32_16x16x32_bf16 v[20:23], v[66:69], v[4:7], v[20:23]
	s_nop 7
	global_store_dwordx4 v[86:87], v[20:23], off offset:64 nt
	ds_read_b128 v[20:23], v64 offset:4608
	s_waitcnt lgkmcnt(0)
	v_mfma_f32_16x16x32_bf16 v[70:73], v[20:23], v[0:3], 0
	v_mfma_f32_16x16x32_bf16 v[70:73], v[74:77], v[4:7], v[70:73]
	s_nop 7
	global_store_dwordx4 v[86:87], v[70:73], off offset:128 nt
	ds_read_b128 v[70:73], v65
	s_waitcnt lgkmcnt(0)
	v_mfma_f32_16x16x32_bf16 v[78:81], v[70:73], v[0:3], 0
	ds_read_b128 v[0:3], v65 offset:64
	s_waitcnt lgkmcnt(0)
	v_mfma_f32_16x16x32_bf16 v[4:7], v[0:3], v[4:7], v[78:81]
	s_nop 7
	global_store_dwordx4 v[86:87], v[4:7], off offset:192 nt
	ds_read_b128 v[4:7], v64 offset:11520
	ds_read_b128 v[78:81], v64 offset:11584
	s_waitcnt lgkmcnt(1)
	v_mfma_f32_16x16x32_bf16 v[82:85], v[8:11], v[4:7], 0
	s_waitcnt lgkmcnt(0)
	v_mfma_f32_16x16x32_bf16 v[82:85], v[16:19], v[78:81], v[82:85]
	s_nop 7
	global_store_dwordx4 v[90:91], v[82:85], off offset:-4096 nt
	s_nop 1
	v_mfma_f32_16x16x32_bf16 v[82:85], v[12:15], v[4:7], 0
	v_mfma_f32_16x16x32_bf16 v[82:85], v[66:69], v[78:81], v[82:85]
	s_nop 7
	global_store_dwordx4 v[88:89], v[82:85], off offset:64 nt
	s_nop 1
	v_mfma_f32_16x16x32_bf16 v[82:85], v[20:23], v[4:7], 0
	v_mfma_f32_16x16x32_bf16 v[4:7], v[70:73], v[4:7], 0
	v_mfma_f32_16x16x32_bf16 v[82:85], v[74:77], v[78:81], v[82:85]
	v_mfma_f32_16x16x32_bf16 v[4:7], v[0:3], v[78:81], v[4:7]
	s_nop 6
	global_store_dwordx4 v[88:89], v[82:85], off offset:128 nt
	global_store_dwordx4 v[88:89], v[4:7], off offset:192 nt
	ds_read_b128 v[4:7], v64 offset:13824
	ds_read_b128 v[78:81], v64 offset:13888
	s_waitcnt lgkmcnt(1)
	v_mfma_f32_16x16x32_bf16 v[82:85], v[8:11], v[4:7], 0
	s_waitcnt lgkmcnt(0)
	v_mfma_f32_16x16x32_bf16 v[82:85], v[16:19], v[78:81], v[82:85]
	s_nop 7
	global_store_dwordx4 v[90:91], v[82:85], off nt
	s_nop 1
	v_mfma_f32_16x16x32_bf16 v[82:85], v[12:15], v[4:7], 0
	v_mfma_f32_16x16x32_bf16 v[82:85], v[66:69], v[78:81], v[82:85]
	s_nop 7
	global_store_dwordx4 v[90:91], v[82:85], off offset:64 nt
	s_nop 1
	v_mfma_f32_16x16x32_bf16 v[82:85], v[20:23], v[4:7], 0
	v_mfma_f32_16x16x32_bf16 v[4:7], v[70:73], v[4:7], 0
	v_mfma_f32_16x16x32_bf16 v[82:85], v[74:77], v[78:81], v[82:85]
	v_mfma_f32_16x16x32_bf16 v[4:7], v[0:3], v[78:81], v[4:7]
	s_nop 6
	global_store_dwordx4 v[90:91], v[82:85], off offset:128 nt
	global_store_dwordx4 v[90:91], v[4:7], off offset:192 nt
	ds_read_b128 v[4:7], v65 offset:9216
	ds_read_b128 v[78:81], v65 offset:9280
	s_waitcnt lgkmcnt(1)
	v_mfma_f32_16x16x32_bf16 v[8:11], v[8:11], v[4:7], 0
	s_waitcnt lgkmcnt(0)
	v_mfma_f32_16x16x32_bf16 v[8:11], v[16:19], v[78:81], v[8:11]
	v_add_co_u32_e64 v16, s[0:1], s46, v86
	s_nop 1
	v_addc_co_u32_e64 v17, s[0:1], 0, v87, s[0:1]
	s_nop 3
	global_store_dwordx4 v[16:17], v[8:11], off nt
	s_nop 1
	v_mfma_f32_16x16x32_bf16 v[8:11], v[12:15], v[4:7], 0
	v_mfma_f32_16x16x32_bf16 v[8:11], v[66:69], v[78:81], v[8:11]
	s_nop 7
	global_store_dwordx4 v[16:17], v[8:11], off offset:64 nt
	s_nop 1
	v_mfma_f32_16x16x32_bf16 v[8:11], v[20:23], v[4:7], 0
	v_mfma_f32_16x16x32_bf16 v[4:7], v[70:73], v[4:7], 0
	v_mfma_f32_16x16x32_bf16 v[8:11], v[74:77], v[78:81], v[8:11]
	v_mfma_f32_16x16x32_bf16 v[0:3], v[0:3], v[78:81], v[4:7]
	s_nop 6
	global_store_dwordx4 v[16:17], v[8:11], off offset:128 nt
	global_store_dwordx4 v[16:17], v[0:3], off offset:192 nt
	s_waitcnt lgkmcnt(0)
	s_cbranch_scc0 .LBB0_341
	s_nop 0
	v_and_b32_e32 v0, 56, v27
	v_lshlrev_b32_e32 v1, 2, v248
	s_mov_b32 s38, 0x24000
	s_mov_b32 s37, 0xc000
	s_mov_b32 s36, 0x18000
	v_xor_b32_e32 v4, 4, v1
	v_xor_b32_e32 v5, 8, v1
	v_xor_b32_e32 v6, 16, v1
	v_xor_b32_e32 v7, 32, v1
	v_xor_b32_e32 v8, 64, v1
	v_xor_b32_e32 v9, 0x80, v1
	v_cmp_eq_u32_e32 vcc, 0, v248
	v_lshlrev_b32_e32 v32, 1, v0
	s_mov_b32 s12, s16
	s_branch .LBB0_344
